# v17 + SwiGLU GEMM epilogues issue the same f32 ops as packed v_pk_mul_f32/v_pk_add_f32 on adjacent accumulator pairs (bitwise same results)
# speedup vs baseline: 1.0569x; 1.0008x over previous
; #define PG8_STAGE(bufoff, gbase, voff) do { _Pragma("unroll") for (int _i = 0; _i < 2; ++_i) \
;         __builtin_amdgcn_global_load_lds((const unsigned*)((const char*)(gbase) + (voff)[_i]), (LAS unsigned*)(lds + (bufoff) + ldsw + _i * 8192), 16, 0, 0); } while (0)
; #define PG8_LDA(dst, b, h) do { _Pragma("unroll") for (int m = 0; m < 4; ++m) _Pragma("unroll") for (int k = 0; k < 2; ++k) dst[m][k] = *(const LAS bf16x8*)(lds + PG8_SA(b, h) + aoff + m * 2048 + k * 1024); } while (0)
; #define PG8_LDB(dst, b, h) do { _Pragma("unroll") for (int n = 0; n < 2; ++n) _Pragma("unroll") for (int k = 0; k < 2; ++k) dst[n][k] = *(const LAS bf16x8*)(lds + PG8_SB(b, h) + boff + n * 2048 + k * 1024); } while (0)
; #define PG8_MMA(ai, bj, At, Bt) do { __builtin_amdgcn_s_setprio(1); _Pragma("unroll") for (int m = 0; m < 4; ++m) _Pragma("unroll") for (int n = 0; n < 2; ++n) _Pragma("unroll") for (int k = 0; k < 2; ++k) \
;         acc[ai][bj][m][n] = __builtin_amdgcn_mfma_f32_16x16x32_bf16(Bt[n][k], At[m][k], acc[ai][bj][m][n], 0, 0, 0); __builtin_amdgcn_s_setprio(0); } while (0)
; #define PG8_WAIT_L(n) asm volatile("s_waitcnt lgkmcnt(" #n ")" ::: "memory")
; #define PG8_BAR __builtin_amdgcn_s_barrier()
; #define PG8_SCHED __builtin_amdgcn_sched_barrier(0)
; template <class Epi>
; __device__ __forceinline__ void gemm_phase(LAS unsigned char* lds, const Gemm g, const Sched& S, const Epi& E) {
;     ...
;             PG8_LDB(B0, 0, 0); PG8_SCHED; PG8_LDA(At, 0, 0); PG8_STAGE(PG8_SA(1, 1), a1 + hstepA, voffA);
;             PG8_WAIT_L(8); PG8_BAR; PG8_WAIT_L(0); PG8_MMA(0, 0, At, B0); PG8_BAR; PG8_SCHED;
;             PG8_LDB(B1, 0, 1); PG8_STAGE(PG8_SB(0, 0), b2, voffB);
;             PG8_BAR; PG8_WAIT_L(0); PG8_MMA(0, 1, At, B1); PG8_BAR;
;             PG8_LDA(At, 0, 1); PG8_STAGE(PG8_SA(0, 0), a2, voffA);
;             PG8_BAR; PG8_WAIT_L(0); PG8_MMA(1, 0, At, B0); PG8_BAR; PG8_SCHED;
.LBB0_177:
	v_add_u32_e32 v162, s62, v148
	s_add_u32 s38, s10, s24
	ds_read_b128 v[150:153], v162
	ds_read_b128 v[154:157], v162 offset:1024
	ds_read_b128 v[158:161], v162 offset:2048
	ds_read_b128 v[162:165], v162 offset:3072
	s_addc_u32 s39, s11, s25
	s_add_u32 s38, s38, 0x100
	s_addc_u32 s39, s39, 0
	s_add_u32 s71, s9, s24
	s_addc_u32 s80, s51, s25
	s_cmpk_eq_i32 s24, 0xf00
	s_cselect_b32 s53, s19, s39
	s_cselect_b32 s52, s66, s38
	s_cselect_b32 s39, s17, s80
	s_cselect_b32 s38, s67, s71
	v_lshl_add_u64 v[190:191], v[144:145], 0, s[24:25]
	s_add_i32 m0, s35, 0xc000
	ds_read_b128 v[166:169], v149
	ds_read_b128 v[170:173], v149 offset:1024
	ds_read_b128 v[174:177], v149 offset:2048
	ds_read_b128 v[178:181], v149 offset:3072
	ds_read_b128 v[182:185], v149 offset:4096
	ds_read_b128 v[186:189], v149 offset:5120
	ds_read_b128 v[194:197], v149 offset:6144
	ds_read_b128 v[198:201], v149 offset:7168
	global_load_lds_dwordx4 v[190:191], off
	v_lshl_add_u64 v[190:191], v[146:147], 0, s[24:25]
	s_add_i32 m0, s35, 0xe000
	s_nop 0
	global_load_lds_dwordx4 v[190:191], off
	s_waitcnt lgkmcnt(8)
	s_barrier
	s_waitcnt lgkmcnt(0)
	s_setprio 1
	s_waitcnt lgkmcnt(0)
	v_mfma_f32_16x16x32_bf16 v[124:127], v[150:153], v[166:169], v[124:127]
	v_mfma_f32_16x16x32_bf16 v[120:123], v[158:161], v[166:169], v[120:123]
	v_mfma_f32_16x16x32_bf16 v[116:119], v[150:153], v[174:177], v[116:119]
	v_mfma_f32_16x16x32_bf16 v[112:115], v[158:161], v[174:177], v[112:115]
	v_mfma_f32_16x16x32_bf16 v[108:111], v[150:153], v[182:185], v[108:111]
	v_mfma_f32_16x16x32_bf16 v[104:107], v[158:161], v[182:185], v[104:107]
	v_mfma_f32_16x16x32_bf16 v[100:103], v[150:153], v[194:197], v[100:103]
	v_mfma_f32_16x16x32_bf16 v[96:99], v[158:161], v[194:197], v[96:99]
	v_mfma_f32_16x16x32_bf16 v[124:127], v[154:157], v[170:173], v[124:127]
	v_mfma_f32_16x16x32_bf16 v[120:123], v[162:165], v[170:173], v[120:123]
	v_mfma_f32_16x16x32_bf16 v[116:119], v[154:157], v[178:181], v[116:119]
	v_mfma_f32_16x16x32_bf16 v[112:115], v[162:165], v[178:181], v[112:115]
	v_mfma_f32_16x16x32_bf16 v[108:111], v[154:157], v[186:189], v[108:111]
	v_mfma_f32_16x16x32_bf16 v[104:107], v[162:165], v[186:189], v[104:107]
	v_mfma_f32_16x16x32_bf16 v[100:103], v[154:157], v[198:201], v[100:103]
	v_mfma_f32_16x16x32_bf16 v[96:99], v[162:165], v[198:201], v[96:99]
	s_setprio 0
	s_barrier
	v_add_u32_e32 v190, s63, v148
	s_add_i32 s71, s62, s1
	ds_read_b128 v[202:205], v190
	ds_read_b128 v[206:209], v190 offset:1024
	ds_read_b128 v[210:213], v190 offset:2048
	ds_read_b128 v[214:217], v190 offset:3072
	v_lshl_add_u64 v[190:191], s[38:39], 0, v[130:131]
	s_mov_b32 m0, s71
	v_lshl_add_u64 v[218:219], s[38:39], 0, v[128:129]
	global_load_lds_dwordx4 v[190:191], off
	s_add_i32 m0, s71, 0x2000
	s_nop 0
	global_load_lds_dwordx4 v[218:219], off
	s_barrier
	s_waitcnt lgkmcnt(0)
	s_setprio 1
	s_waitcnt lgkmcnt(0)
	v_mfma_f32_16x16x32_bf16 v[92:95], v[202:205], v[166:169], v[92:95]
	v_mfma_f32_16x16x32_bf16 v[88:91], v[210:213], v[166:169], v[88:91]
	v_mfma_f32_16x16x32_bf16 v[84:87], v[202:205], v[174:177], v[84:87]
	v_mfma_f32_16x16x32_bf16 v[80:83], v[210:213], v[174:177], v[80:83]
	v_mfma_f32_16x16x32_bf16 v[76:79], v[202:205], v[182:185], v[76:79]
	v_mfma_f32_16x16x32_bf16 v[72:75], v[210:213], v[182:185], v[72:75]
	v_mfma_f32_16x16x32_bf16 v[68:71], v[202:205], v[194:197], v[68:71]
	v_mfma_f32_16x16x32_bf16 v[64:67], v[210:213], v[194:197], v[64:67]
	v_mfma_f32_16x16x32_bf16 v[92:95], v[206:209], v[170:173], v[92:95]
	v_mfma_f32_16x16x32_bf16 v[88:91], v[214:217], v[170:173], v[88:91]
	v_mfma_f32_16x16x32_bf16 v[84:87], v[206:209], v[178:181], v[84:87]
	v_mfma_f32_16x16x32_bf16 v[80:83], v[214:217], v[178:181], v[80:83]
	v_mfma_f32_16x16x32_bf16 v[76:79], v[206:209], v[186:189], v[76:79]
	v_mfma_f32_16x16x32_bf16 v[72:75], v[214:217], v[186:189], v[72:75]
	v_mfma_f32_16x16x32_bf16 v[68:71], v[206:209], v[198:201], v[68:71]
	v_mfma_f32_16x16x32_bf16 v[64:67], v[214:217], v[198:201], v[64:67]
	s_setprio 0
	s_mov_b32 m0, s35
	v_lshl_add_u64 v[220:221], s[52:53], 0, v[130:131]
	s_barrier
	ds_read_b128 v[166:169], v149 offset:16384
	ds_read_b128 v[170:173], v149 offset:17408
	ds_read_b128 v[174:177], v149 offset:18432
	ds_read_b128 v[178:181], v149 offset:19456
	ds_read_b128 v[182:185], v149 offset:20480
	ds_read_b128 v[186:189], v149 offset:21504
	ds_read_b128 v[194:197], v149 offset:22528
	ds_read_b128 v[198:201], v149 offset:23552
	global_load_lds_dwordx4 v[220:221], off
	v_lshl_add_u64 v[222:223], s[52:53], 0, v[128:129]
	s_mov_b32 m0, s43
	s_nop 0
	global_load_lds_dwordx4 v[222:223], off
	s_barrier
	s_waitcnt lgkmcnt(0)
	s_setprio 1
	s_waitcnt lgkmcnt(0)
	v_mfma_f32_16x16x32_bf16 v[60:63], v[150:153], v[166:169], v[60:63]
	v_mfma_f32_16x16x32_bf16 v[56:59], v[158:161], v[166:169], v[56:59]
	v_mfma_f32_16x16x32_bf16 v[52:55], v[150:153], v[174:177], v[52:55]
	v_mfma_f32_16x16x32_bf16 v[48:51], v[158:161], v[174:177], v[48:51]
	v_mfma_f32_16x16x32_bf16 v[44:47], v[150:153], v[182:185], v[44:47]
	v_mfma_f32_16x16x32_bf16 v[40:43], v[158:161], v[182:185], v[40:43]
	v_mfma_f32_16x16x32_bf16 v[36:39], v[150:153], v[194:197], v[36:39]
	v_mfma_f32_16x16x32_bf16 v[32:35], v[158:161], v[194:197], v[32:35]
	v_mfma_f32_16x16x32_bf16 v[60:63], v[154:157], v[170:173], v[60:63]
	v_mfma_f32_16x16x32_bf16 v[56:59], v[162:165], v[170:173], v[56:59]
	v_mfma_f32_16x16x32_bf16 v[52:55], v[154:157], v[178:181], v[52:55]
	v_mfma_f32_16x16x32_bf16 v[48:51], v[162:165], v[178:181], v[48:51]
	v_mfma_f32_16x16x32_bf16 v[44:47], v[154:157], v[186:189], v[44:47]
	v_mfma_f32_16x16x32_bf16 v[40:43], v[162:165], v[186:189], v[40:43]
	v_mfma_f32_16x16x32_bf16 v[36:39], v[154:157], v[198:201], v[36:39]
	v_mfma_f32_16x16x32_bf16 v[32:35], v[162:165], v[198:201], v[32:35]
	s_setprio 0
	s_barrier
; #define PG8_STAGE(bufoff, gbase, voff) do { _Pragma("unroll") for (int _i = 0; _i < 2; ++_i) \
;         __builtin_amdgcn_global_load_lds((const unsigned*)((const char*)(gbase) + (voff)[_i]), (LAS unsigned*)(lds + (bufoff) + ldsw + _i * 8192), 16, 0, 0); } while (0)
; #define PG8_LDA(dst, b, h) do { _Pragma("unroll") for (int m = 0; m < 4; ++m) _Pragma("unroll") for (int k = 0; k < 2; ++k) dst[m][k] = *(const LAS bf16x8*)(lds + PG8_SA(b, h) + aoff + m * 2048 + k * 1024); } while (0)
; #define PG8_LDB(dst, b, h) do { _Pragma("unroll") for (int n = 0; n < 2; ++n) _Pragma("unroll") for (int k = 0; k < 2; ++k) dst[n][k] = *(const LAS bf16x8*)(lds + PG8_SB(b, h) + boff + n * 2048 + k * 1024); } while (0)
; #define PG8_MMA(ai, bj, At, Bt) do { __builtin_amdgcn_s_setprio(1); _Pragma("unroll") for (int m = 0; m < 4; ++m) _Pragma("unroll") for (int n = 0; n < 2; ++n) _Pragma("unroll") for (int k = 0; k < 2; ++k) \
;         acc[ai][bj][m][n] = __builtin_amdgcn_mfma_f32_16x16x32_bf16(Bt[n][k], At[m][k], acc[ai][bj][m][n], 0, 0, 0); __builtin_amdgcn_s_setprio(0); } while (0)
; #define PG8_WAIT_V(n) asm volatile("s_waitcnt vmcnt(" #n ")" ::: "memory")
; #define PG8_WAIT_L(n) asm volatile("s_waitcnt lgkmcnt(" #n ")" ::: "memory")
; #define PG8_BAR __builtin_amdgcn_s_barrier()
; #define PG8_SCHED __builtin_amdgcn_sched_barrier(0)
; template <class Epi>
; __device__ __forceinline__ void gemm_phase(LAS unsigned char* lds, const Gemm g, const Sched& S, const Epi& E) {
;     ...
;             PG8_STAGE(PG8_SB(0, 1), b2 + hstepB, voffB);
;             PG8_WAIT_V(6); PG8_BAR; PG8_MMA(1, 1, At, B1); PG8_BAR;
;             PG8_LDB(B0, 1, 0); PG8_SCHED; PG8_LDA(At, 1, 0); PG8_STAGE(PG8_SA(0, 1), a2 + hstepA, voffA);
;             PG8_WAIT_L(8); PG8_BAR; PG8_WAIT_L(0); PG8_MMA(0, 0, At, B0); PG8_BAR; PG8_SCHED;
;             PG8_LDB(B1, 1, 1); PG8_STAGE(PG8_SB(1, 0), b3, voffB);
;             PG8_BAR; PG8_WAIT_L(0); PG8_MMA(0, 1, At, B1); PG8_BAR;
;             PG8_LDA(At, 1, 1); PG8_STAGE(PG8_SA(1, 0), a3, voffA);
;             PG8_BAR; PG8_WAIT_L(0); PG8_MMA(1, 0, At, B0); PG8_BAR; PG8_SCHED;
	s_add_u32 s80, s38, 0x80000
	s_addc_u32 s81, s39, 0
	s_add_i32 s71, s63, s1
	v_lshl_add_u64 v[150:151], s[80:81], 0, v[130:131]
	s_mov_b32 m0, s71
	s_nop 0
	global_load_lds_dwordx4 v[150:151], off
	v_lshl_add_u64 v[150:151], s[80:81], 0, v[128:129]
	s_add_i32 m0, s71, 0x2000
	s_nop 0
	global_load_lds_dwordx4 v[150:151], off
	s_waitcnt vmcnt(6)
	s_barrier
	s_setprio 1
	v_mfma_f32_16x16x32_bf16 v[28:31], v[202:205], v[166:169], v[28:31]
	v_mfma_f32_16x16x32_bf16 v[24:27], v[210:213], v[166:169], v[24:27]
	v_mfma_f32_16x16x32_bf16 v[20:23], v[202:205], v[174:177], v[20:23]
	v_mfma_f32_16x16x32_bf16 v[16:19], v[210:213], v[174:177], v[16:19]
	v_mfma_f32_16x16x32_bf16 v[12:15], v[202:205], v[182:185], v[12:15]
	v_mfma_f32_16x16x32_bf16 v[8:11], v[210:213], v[182:185], v[8:11]
	v_mfma_f32_16x16x32_bf16 v[4:7], v[202:205], v[194:197], v[4:7]
	v_mfma_f32_16x16x32_bf16 v[0:3], v[210:213], v[194:197], v[0:3]
	v_mfma_f32_16x16x32_bf16 v[28:31], v[206:209], v[170:173], v[28:31]
	v_mfma_f32_16x16x32_bf16 v[24:27], v[214:217], v[170:173], v[24:27]
	v_mfma_f32_16x16x32_bf16 v[20:23], v[206:209], v[178:181], v[20:23]
	v_mfma_f32_16x16x32_bf16 v[16:19], v[214:217], v[178:181], v[16:19]
	v_mfma_f32_16x16x32_bf16 v[12:15], v[206:209], v[186:189], v[12:15]
	v_mfma_f32_16x16x32_bf16 v[8:11], v[214:217], v[186:189], v[8:11]
	v_mfma_f32_16x16x32_bf16 v[4:7], v[206:209], v[198:201], v[4:7]
	v_mfma_f32_16x16x32_bf16 v[0:3], v[214:217], v[198:201], v[0:3]
	s_setprio 0
	s_add_i32 s71, 0, 0x18000
	v_add_u32_e32 v162, s71, v148
	s_barrier
	ds_read_b128 v[150:153], v162
	ds_read_b128 v[154:157], v162 offset:1024
	ds_read_b128 v[158:161], v162 offset:2048
	ds_read_b128 v[162:165], v162 offset:3072
	s_add_u32 s52, s52, 0x80000
	s_addc_u32 s53, s53, 0
	s_mov_b32 m0, s54
	v_lshl_add_u64 v[202:203], s[52:53], 0, v[130:131]
	ds_read_b128 v[166:169], v149 offset:32768
	ds_read_b128 v[170:173], v149 offset:33792
	ds_read_b128 v[174:177], v149 offset:34816
	ds_read_b128 v[178:181], v149 offset:35840
	ds_read_b128 v[182:185], v149 offset:36864
	ds_read_b128 v[186:189], v149 offset:37888
	ds_read_b128 v[194:197], v149 offset:38912
	ds_read_b128 v[198:201], v149 offset:39936
	global_load_lds_dwordx4 v[202:203], off
	v_lshl_add_u64 v[202:203], s[52:53], 0, v[128:129]
	s_mov_b32 m0, s55
	s_nop 0
	global_load_lds_dwordx4 v[202:203], off
	s_waitcnt lgkmcnt(8)
	s_barrier
	s_waitcnt lgkmcnt(0)
	s_setprio 1
	s_waitcnt lgkmcnt(0)
	v_mfma_f32_16x16x32_bf16 v[124:127], v[150:153], v[166:169], v[124:127]
	v_mfma_f32_16x16x32_bf16 v[120:123], v[158:161], v[166:169], v[120:123]
	v_mfma_f32_16x16x32_bf16 v[116:119], v[150:153], v[174:177], v[116:119]
	v_mfma_f32_16x16x32_bf16 v[112:115], v[158:161], v[174:177], v[112:115]
	v_mfma_f32_16x16x32_bf16 v[108:111], v[150:153], v[182:185], v[108:111]
	v_mfma_f32_16x16x32_bf16 v[104:107], v[158:161], v[182:185], v[104:107]
	v_mfma_f32_16x16x32_bf16 v[100:103], v[150:153], v[194:197], v[100:103]
	v_mfma_f32_16x16x32_bf16 v[96:99], v[158:161], v[194:197], v[96:99]
	v_mfma_f32_16x16x32_bf16 v[124:127], v[154:157], v[170:173], v[124:127]
	v_mfma_f32_16x16x32_bf16 v[120:123], v[162:165], v[170:173], v[120:123]
	v_mfma_f32_16x16x32_bf16 v[116:119], v[154:157], v[178:181], v[116:119]
	v_mfma_f32_16x16x32_bf16 v[112:115], v[162:165], v[178:181], v[112:115]
	v_mfma_f32_16x16x32_bf16 v[108:111], v[154:157], v[186:189], v[108:111]
	v_mfma_f32_16x16x32_bf16 v[104:107], v[162:165], v[186:189], v[104:107]
	v_mfma_f32_16x16x32_bf16 v[100:103], v[154:157], v[198:201], v[100:103]
	v_mfma_f32_16x16x32_bf16 v[96:99], v[162:165], v[198:201], v[96:99]
	s_setprio 0
	s_barrier
	s_add_i32 s52, 0, 0x1c000
	s_add_i32 s53, s71, s1
	v_add_u32_e32 v214, s52, v148
	v_lshl_add_u64 v[190:191], v[190:191], 0, s[14:15]
	s_mov_b32 m0, s53
	ds_read_b128 v[202:205], v214
	ds_read_b128 v[206:209], v214 offset:1024
	ds_read_b128 v[210:213], v214 offset:2048
	ds_read_b128 v[214:217], v214 offset:3072
	global_load_lds_dwordx4 v[190:191], off
	v_lshl_add_u64 v[190:191], v[218:219], 0, s[14:15]
	s_add_i32 m0, s53, 0x2000
	s_nop 0
	global_load_lds_dwordx4 v[190:191], off
	s_barrier
	s_waitcnt lgkmcnt(0)
	s_setprio 1
	s_waitcnt lgkmcnt(0)
	v_mfma_f32_16x16x32_bf16 v[92:95], v[202:205], v[166:169], v[92:95]
	v_mfma_f32_16x16x32_bf16 v[88:91], v[210:213], v[166:169], v[88:91]
	v_mfma_f32_16x16x32_bf16 v[84:87], v[202:205], v[174:177], v[84:87]
	v_mfma_f32_16x16x32_bf16 v[80:83], v[210:213], v[174:177], v[80:83]
	v_mfma_f32_16x16x32_bf16 v[76:79], v[202:205], v[182:185], v[76:79]
	v_mfma_f32_16x16x32_bf16 v[72:75], v[210:213], v[182:185], v[72:75]
	v_mfma_f32_16x16x32_bf16 v[68:71], v[202:205], v[194:197], v[68:71]
	v_mfma_f32_16x16x32_bf16 v[64:67], v[210:213], v[194:197], v[64:67]
	v_mfma_f32_16x16x32_bf16 v[92:95], v[206:209], v[170:173], v[92:95]
	v_mfma_f32_16x16x32_bf16 v[88:91], v[214:217], v[170:173], v[88:91]
	v_mfma_f32_16x16x32_bf16 v[84:87], v[206:209], v[178:181], v[84:87]
	v_mfma_f32_16x16x32_bf16 v[80:83], v[214:217], v[178:181], v[80:83]
	v_mfma_f32_16x16x32_bf16 v[76:79], v[206:209], v[186:189], v[76:79]
	v_mfma_f32_16x16x32_bf16 v[72:75], v[214:217], v[186:189], v[72:75]
	v_mfma_f32_16x16x32_bf16 v[68:71], v[206:209], v[198:201], v[68:71]
	v_mfma_f32_16x16x32_bf16 v[64:67], v[214:217], v[198:201], v[64:67]
	s_setprio 0
	s_mov_b32 m0, s59
	v_lshl_add_u64 v[190:191], v[220:221], 0, s[14:15]
	s_barrier
	ds_read_b128 v[166:169], v149 offset:49152
	ds_read_b128 v[170:173], v149 offset:50176
	ds_read_b128 v[174:177], v149 offset:51200
	ds_read_b128 v[178:181], v149 offset:52224
	ds_read_b128 v[182:185], v149 offset:53248
	ds_read_b128 v[186:189], v149 offset:54272
	ds_read_b128 v[194:197], v149 offset:55296
	ds_read_b128 v[198:201], v149 offset:56320
	global_load_lds_dwordx4 v[190:191], off
	v_lshl_add_u64 v[190:191], v[222:223], 0, s[14:15]
	s_mov_b32 m0, s61
	s_nop 0
	global_load_lds_dwordx4 v[190:191], off
	s_barrier
; __device__ __forceinline__ unsigned cvt_pk_bf16(float lo, float hi) { unsigned r; asm volatile("v_cvt_pk_bf16_f32 %0, %1, %2" : "=v"(r) : "v"(lo), "v"(hi)); return r; }
; #define PG8_STAGE(bufoff, gbase, voff) do { _Pragma("unroll") for (int _i = 0; _i < 2; ++_i) \
;         __builtin_amdgcn_global_load_lds((const unsigned*)((const char*)(gbase) + (voff)[_i]), (LAS unsigned*)(lds + (bufoff) + ldsw + _i * 8192), 16, 0, 0); } while (0)
; #define PG8_MMA(ai, bj, At, Bt) do { __builtin_amdgcn_s_setprio(1); _Pragma("unroll") for (int m = 0; m < 4; ++m) _Pragma("unroll") for (int n = 0; n < 2; ++n) _Pragma("unroll") for (int k = 0; k < 2; ++k) \
;         acc[ai][bj][m][n] = __builtin_amdgcn_mfma_f32_16x16x32_bf16(Bt[n][k], At[m][k], acc[ai][bj][m][n], 0, 0, 0); __builtin_amdgcn_s_setprio(0); } while (0)
; #define PG8_WAIT_V(n) asm volatile("s_waitcnt vmcnt(" #n ")" ::: "memory")
; #define PG8_BAR __builtin_amdgcn_s_barrier()
; template <class Epi>
; __device__ __forceinline__ void gemm_phase(LAS unsigned char* lds, const Gemm g, const Sched& S, const Epi& E) {
;     ...
;             PG8_STAGE(PG8_SB(1, 1), b3 + hstepB, voffB);
;             PG8_WAIT_V(6); PG8_BAR; PG8_MMA(1, 1, At, B1); PG8_BAR;
;     __device__ __forceinline__ void operator()(AccRef acc, const Unit& u, int wr, int wc, int fr, int fq) const {
;     ...
;             for (int m = 0; m < 4; ++m) { const size_t row = (size_t)u.pm * 256 + ai * 128 + wr * 64 + m * 16 + fr; float o[8];
; #pragma unroll
;                 for (int bj = 0; bj < 2; ++bj) { const f32x4 gg = acc[ai][bj][m][0], uu = acc[ai][bj][m][1];
; #pragma unroll
;                     for (int j = 0; j < 4; ++j) o[4 * bj + j] = gg[j] * __builtin_amdgcn_rcpf(1.0f + __expf(-gg[j])) * uu[j]; }
;                 u32x4 w; w.x = cvt_pk_bf16(o[0], o[1]); w.y = cvt_pk_bf16(o[2], o[3]); w.z = cvt_pk_bf16(o[4], o[5]); w.w = cvt_pk_bf16(o[6], o[7]);
;                 *(u32x4*)(act + row * FF_ + (u.pn * 4 + wc) * 32 + 8 * fq) = w; }
	s_waitcnt lgkmcnt(0)
	s_setprio 1
	s_waitcnt lgkmcnt(0)
	v_mfma_f32_16x16x32_bf16 v[60:63], v[150:153], v[166:169], v[60:63]
	v_mfma_f32_16x16x32_bf16 v[56:59], v[158:161], v[166:169], v[56:59]
	v_mfma_f32_16x16x32_bf16 v[52:55], v[150:153], v[174:177], v[52:55]
	v_mfma_f32_16x16x32_bf16 v[48:51], v[158:161], v[174:177], v[48:51]
	v_mfma_f32_16x16x32_bf16 v[44:47], v[150:153], v[182:185], v[44:47]
	v_mfma_f32_16x16x32_bf16 v[40:43], v[158:161], v[182:185], v[40:43]
	v_mfma_f32_16x16x32_bf16 v[36:39], v[150:153], v[194:197], v[36:39]
	v_mfma_f32_16x16x32_bf16 v[32:35], v[158:161], v[194:197], v[32:35]
	v_mfma_f32_16x16x32_bf16 v[60:63], v[154:157], v[170:173], v[60:63]
	v_mfma_f32_16x16x32_bf16 v[56:59], v[162:165], v[170:173], v[56:59]
	v_mfma_f32_16x16x32_bf16 v[52:55], v[154:157], v[178:181], v[52:55]
	v_mfma_f32_16x16x32_bf16 v[48:51], v[162:165], v[178:181], v[48:51]
	v_mfma_f32_16x16x32_bf16 v[44:47], v[154:157], v[186:189], v[44:47]
	v_mfma_f32_16x16x32_bf16 v[40:43], v[162:165], v[186:189], v[40:43]
	v_mfma_f32_16x16x32_bf16 v[36:39], v[154:157], v[198:201], v[36:39]
	v_mfma_f32_16x16x32_bf16 v[32:35], v[162:165], v[198:201], v[32:35]
	s_setprio 0
	s_barrier
	s_add_u32 s38, s38, 0x80080
	s_addc_u32 s39, s39, 0
	s_add_i32 s52, s52, s1
	v_lshl_add_u64 v[150:151], s[38:39], 0, v[130:131]
	s_mov_b32 m0, s52
	s_nop 0
	global_load_lds_dwordx4 v[150:151], off
	v_lshl_add_u64 v[150:151], s[38:39], 0, v[128:129]
	s_add_i32 m0, s52, 0x2000
	s_nop 0
	global_load_lds_dwordx4 v[150:151], off
	s_waitcnt vmcnt(6)
	s_barrier
	s_setprio 1
	v_mfma_f32_16x16x32_bf16 v[28:31], v[202:205], v[166:169], v[28:31]
	v_mfma_f32_16x16x32_bf16 v[24:27], v[210:213], v[166:169], v[24:27]
	v_mfma_f32_16x16x32_bf16 v[20:23], v[202:205], v[174:177], v[20:23]
	v_mfma_f32_16x16x32_bf16 v[16:19], v[210:213], v[174:177], v[16:19]
	v_mfma_f32_16x16x32_bf16 v[12:15], v[202:205], v[182:185], v[12:15]
	v_mfma_f32_16x16x32_bf16 v[8:11], v[210:213], v[182:185], v[8:11]
	v_mfma_f32_16x16x32_bf16 v[4:7], v[202:205], v[194:197], v[4:7]
	v_mfma_f32_16x16x32_bf16 v[0:3], v[210:213], v[194:197], v[0:3]
	v_mfma_f32_16x16x32_bf16 v[28:31], v[206:209], v[170:173], v[28:31]
	v_mfma_f32_16x16x32_bf16 v[24:27], v[214:217], v[170:173], v[24:27]
	v_mfma_f32_16x16x32_bf16 v[20:23], v[206:209], v[178:181], v[20:23]
	v_mfma_f32_16x16x32_bf16 v[16:19], v[214:217], v[178:181], v[16:19]
	v_mfma_f32_16x16x32_bf16 v[12:15], v[206:209], v[186:189], v[12:15]
	v_mfma_f32_16x16x32_bf16 v[8:11], v[214:217], v[186:189], v[8:11]
	v_mfma_f32_16x16x32_bf16 v[4:7], v[206:209], v[198:201], v[4:7]
	v_mfma_f32_16x16x32_bf16 v[0:3], v[214:217], v[198:201], v[0:3]
	s_setprio 0
	s_add_i32 s70, s70, 2
	s_add_u32 s24, s24, 0x100
	s_addc_u32 s25, s25, 0
	s_cmp_gt_u32 s70, 29
	s_barrier
	s_cbranch_scc0 .LBB0_177
	v_mov_b32_e32 v170, 0xbfb8aa3b
	v_mov_b32_e32 v172, 1.0
	s_add_u32 s24, s9, 0xffffff00
	s_addc_u32 s25, s51, -1
	s_ashr_i32 s9, s8, 31
	s_lshl_b64 s[38:39], s[8:9], 8
	v_lshl_add_u64 v[144:145], v[134:135], 0, s[38:39]
	v_mov_b64_e32 v[146:147], s[44:45]
	v_mad_u64_u32 v[146:147], s[52:53], v144, s64, v[146:147]
	s_lshl_b32 s9, s57, 7
	v_mov_b32_e32 v144, v147
	s_or_b32 s38, s9, s58
	v_mad_u64_u32 v[144:145], s[52:53], v145, s64, v[144:145]
	s_ashr_i32 s39, s38, 31
	v_mov_b32_e32 v147, v144
	v_lshl_add_u64 v[144:145], s[38:39], 1, v[146:147]
	v_lshl_add_u64 v[144:145], v[144:145], 0, v[132:133]
	v_pk_mul_f32 v[162:163], v[124:125], v[170:171] op_sel_hi:[1,0]
	v_pk_mul_f32 v[164:165], v[126:127], v[170:171] op_sel_hi:[1,0]
	v_pk_mul_f32 v[166:167], v[92:93], v[170:171] op_sel_hi:[1,0]
	v_pk_mul_f32 v[168:169], v[94:95], v[170:171] op_sel_hi:[1,0]
	v_exp_f32_e32 v162, v162
	v_exp_f32_e32 v163, v163
	v_exp_f32_e32 v164, v164
	v_exp_f32_e32 v165, v165
	v_exp_f32_e32 v166, v166
	v_exp_f32_e32 v167, v167
	v_exp_f32_e32 v168, v168
	v_exp_f32_e32 v169, v169
	v_pk_add_f32 v[162:163], v[162:163], v[172:173] op_sel_hi:[1,0]
	v_pk_add_f32 v[164:165], v[164:165], v[172:173] op_sel_hi:[1,0]
	v_pk_add_f32 v[166:167], v[166:167], v[172:173] op_sel_hi:[1,0]
	v_pk_add_f32 v[168:169], v[168:169], v[172:173] op_sel_hi:[1,0]
	v_rcp_f32_e32 v162, v162
	v_rcp_f32_e32 v163, v163
	v_rcp_f32_e32 v164, v164
	v_rcp_f32_e32 v165, v165
	v_rcp_f32_e32 v166, v166
	v_rcp_f32_e32 v167, v167
	v_rcp_f32_e32 v168, v168
	v_rcp_f32_e32 v169, v169
	v_pk_mul_f32 v[162:163], v[124:125], v[162:163]
	v_pk_mul_f32 v[164:165], v[126:127], v[164:165]
	v_pk_mul_f32 v[166:167], v[92:93], v[166:167]
	v_pk_mul_f32 v[168:169], v[94:95], v[168:169]
	v_pk_mul_f32 v[162:163], v[120:121], v[162:163]
	v_pk_mul_f32 v[164:165], v[122:123], v[164:165]
	v_pk_mul_f32 v[166:167], v[88:89], v[166:167]
	v_pk_mul_f32 v[168:169], v[90:91], v[168:169]
	v_cvt_pk_bf16_f32 v150, v162, v163
	v_cvt_pk_bf16_f32 v151, v164, v165
	v_cvt_pk_bf16_f32 v152, v166, v167
	v_cvt_pk_bf16_f32 v153, v168, v169
	global_store_dwordx4 v[144:145], v[150:153], off
	s_mov_b32 s9, 0x2c000
	v_add_co_u32_e32 v146, vcc, s9, v144
	s_nop 0
	v_addc_co_u32_e32 v147, vcc, 0, v145, vcc
	v_pk_mul_f32 v[162:163], v[116:117], v[170:171] op_sel_hi:[1,0]
	v_pk_mul_f32 v[164:165], v[118:119], v[170:171] op_sel_hi:[1,0]
	v_pk_mul_f32 v[166:167], v[84:85], v[170:171] op_sel_hi:[1,0]
	v_pk_mul_f32 v[168:169], v[86:87], v[170:171] op_sel_hi:[1,0]
	v_exp_f32_e32 v162, v162
	v_exp_f32_e32 v163, v163
	v_exp_f32_e32 v164, v164
	v_exp_f32_e32 v165, v165
	v_exp_f32_e32 v166, v166
	v_exp_f32_e32 v167, v167
	v_exp_f32_e32 v168, v168
	v_exp_f32_e32 v169, v169
	v_pk_add_f32 v[162:163], v[162:163], v[172:173] op_sel_hi:[1,0]
	v_pk_add_f32 v[164:165], v[164:165], v[172:173] op_sel_hi:[1,0]
	v_pk_add_f32 v[166:167], v[166:167], v[172:173] op_sel_hi:[1,0]
; __device__ __forceinline__ unsigned cvt_pk_bf16(float lo, float hi) { unsigned r; asm volatile("v_cvt_pk_bf16_f32 %0, %1, %2" : "=v"(r) : "v"(lo), "v"(hi)); return r; }
;     __device__ __forceinline__ void operator()(AccRef acc, const Unit& u, int wr, int wc, int fr, int fq) const {
;     ...
;             for (int m = 0; m < 4; ++m) { const size_t row = (size_t)u.pm * 256 + ai * 128 + wr * 64 + m * 16 + fr; float o[8];
; #pragma unroll
;                 for (int bj = 0; bj < 2; ++bj) { const f32x4 gg = acc[ai][bj][m][0], uu = acc[ai][bj][m][1];
; #pragma unroll
;                     for (int j = 0; j < 4; ++j) o[4 * bj + j] = gg[j] * __builtin_amdgcn_rcpf(1.0f + __expf(-gg[j])) * uu[j]; }
;                 u32x4 w; w.x = cvt_pk_bf16(o[0], o[1]); w.y = cvt_pk_bf16(o[2], o[3]); w.z = cvt_pk_bf16(o[4], o[5]); w.w = cvt_pk_bf16(o[6], o[7]);
;                 *(u32x4*)(act + row * FF_ + (u.pn * 4 + wc) * 32 + 8 * fq) = w; }
	v_pk_add_f32 v[168:169], v[168:169], v[172:173] op_sel_hi:[1,0]
	v_rcp_f32_e32 v162, v162
	v_rcp_f32_e32 v163, v163
	v_rcp_f32_e32 v164, v164
	v_rcp_f32_e32 v165, v165
	v_rcp_f32_e32 v166, v166
	v_rcp_f32_e32 v167, v167
	v_rcp_f32_e32 v168, v168
	v_rcp_f32_e32 v169, v169
	v_pk_mul_f32 v[162:163], v[116:117], v[162:163]
	v_pk_mul_f32 v[164:165], v[118:119], v[164:165]
	v_pk_mul_f32 v[166:167], v[84:85], v[166:167]
	v_pk_mul_f32 v[168:169], v[86:87], v[168:169]
	v_pk_mul_f32 v[162:163], v[112:113], v[162:163]
	v_pk_mul_f32 v[164:165], v[114:115], v[164:165]
	v_pk_mul_f32 v[166:167], v[80:81], v[166:167]
	v_pk_mul_f32 v[168:169], v[82:83], v[168:169]
	v_cvt_pk_bf16_f32 v150, v162, v163
	v_cvt_pk_bf16_f32 v151, v164, v165
	v_cvt_pk_bf16_f32 v152, v166, v167
	v_cvt_pk_bf16_f32 v153, v168, v169
	global_store_dwordx4 v[146:147], v[150:153], off
	s_mov_b32 s9, 0x58000
	v_add_co_u32_e32 v146, vcc, s9, v144
	s_nop 0
	v_addc_co_u32_e32 v147, vcc, 0, v145, vcc
	v_pk_mul_f32 v[162:163], v[108:109], v[170:171] op_sel_hi:[1,0]
	v_pk_mul_f32 v[164:165], v[110:111], v[170:171] op_sel_hi:[1,0]
	v_pk_mul_f32 v[166:167], v[76:77], v[170:171] op_sel_hi:[1,0]
	v_pk_mul_f32 v[168:169], v[78:79], v[170:171] op_sel_hi:[1,0]
	v_exp_f32_e32 v162, v162
	v_exp_f32_e32 v163, v163
	v_exp_f32_e32 v164, v164
	v_exp_f32_e32 v165, v165
	v_exp_f32_e32 v166, v166
	v_exp_f32_e32 v167, v167
	v_exp_f32_e32 v168, v168
	v_exp_f32_e32 v169, v169
	v_pk_add_f32 v[162:163], v[162:163], v[172:173] op_sel_hi:[1,0]
	v_pk_add_f32 v[164:165], v[164:165], v[172:173] op_sel_hi:[1,0]
	v_pk_add_f32 v[166:167], v[166:167], v[172:173] op_sel_hi:[1,0]
	v_pk_add_f32 v[168:169], v[168:169], v[172:173] op_sel_hi:[1,0]
	v_rcp_f32_e32 v162, v162
	v_rcp_f32_e32 v163, v163
	v_rcp_f32_e32 v164, v164
	v_rcp_f32_e32 v165, v165
	v_rcp_f32_e32 v166, v166
	v_rcp_f32_e32 v167, v167
	v_rcp_f32_e32 v168, v168
	v_rcp_f32_e32 v169, v169
	v_pk_mul_f32 v[162:163], v[108:109], v[162:163]
	v_pk_mul_f32 v[164:165], v[110:111], v[164:165]
	v_pk_mul_f32 v[166:167], v[76:77], v[166:167]
	v_pk_mul_f32 v[168:169], v[78:79], v[168:169]
	v_pk_mul_f32 v[162:163], v[104:105], v[162:163]
	v_pk_mul_f32 v[164:165], v[106:107], v[164:165]
	v_pk_mul_f32 v[166:167], v[72:73], v[166:167]
	v_pk_mul_f32 v[168:169], v[74:75], v[168:169]
	v_cvt_pk_bf16_f32 v150, v162, v163
	v_cvt_pk_bf16_f32 v151, v164, v165
	v_cvt_pk_bf16_f32 v152, v166, v167
	v_cvt_pk_bf16_f32 v153, v168, v169
	global_store_dwordx4 v[146:147], v[150:153], off
	s_mov_b32 s9, 0x84000
	v_add_co_u32_e32 v146, vcc, s9, v144
	s_nop 0
	v_addc_co_u32_e32 v147, vcc, 0, v145, vcc
	v_pk_mul_f32 v[162:163], v[100:101], v[170:171] op_sel_hi:[1,0]
	v_pk_mul_f32 v[164:165], v[102:103], v[170:171] op_sel_hi:[1,0]
	v_pk_mul_f32 v[166:167], v[68:69], v[170:171] op_sel_hi:[1,0]
	v_pk_mul_f32 v[168:169], v[70:71], v[170:171] op_sel_hi:[1,0]
	v_exp_f32_e32 v162, v162
	v_exp_f32_e32 v163, v163
	v_exp_f32_e32 v164, v164
	v_exp_f32_e32 v165, v165
	v_exp_f32_e32 v166, v166
	v_exp_f32_e32 v167, v167
	v_exp_f32_e32 v168, v168
	v_exp_f32_e32 v169, v169
	v_pk_add_f32 v[162:163], v[162:163], v[172:173] op_sel_hi:[1,0]
	v_pk_add_f32 v[164:165], v[164:165], v[172:173] op_sel_hi:[1,0]
	v_pk_add_f32 v[166:167], v[166:167], v[172:173] op_sel_hi:[1,0]
	v_pk_add_f32 v[168:169], v[168:169], v[172:173] op_sel_hi:[1,0]
	v_rcp_f32_e32 v162, v162
	v_rcp_f32_e32 v163, v163
	v_rcp_f32_e32 v164, v164
	v_rcp_f32_e32 v165, v165
	v_rcp_f32_e32 v166, v166
	v_rcp_f32_e32 v167, v167
	v_rcp_f32_e32 v168, v168
	v_rcp_f32_e32 v169, v169
	v_pk_mul_f32 v[162:163], v[100:101], v[162:163]
	v_pk_mul_f32 v[164:165], v[102:103], v[164:165]
	v_pk_mul_f32 v[166:167], v[68:69], v[166:167]
	v_pk_mul_f32 v[168:169], v[70:71], v[168:169]
	v_pk_mul_f32 v[162:163], v[96:97], v[162:163]
	v_pk_mul_f32 v[164:165], v[98:99], v[164:165]
	v_pk_mul_f32 v[166:167], v[64:65], v[166:167]
	v_pk_mul_f32 v[168:169], v[66:67], v[168:169]
	v_cvt_pk_bf16_f32 v150, v162, v163
	v_cvt_pk_bf16_f32 v151, v164, v165
	v_cvt_pk_bf16_f32 v152, v166, v167
	v_cvt_pk_bf16_f32 v153, v168, v169
	global_store_dwordx4 v[146:147], v[150:153], off
	s_mov_b32 s9, 0x160000
	v_add_co_u32_e32 v146, vcc, s9, v144
	s_nop 0
	v_addc_co_u32_e32 v147, vcc, 0, v145, vcc
	v_pk_mul_f32 v[162:163], v[60:61], v[170:171] op_sel_hi:[1,0]
	v_pk_mul_f32 v[164:165], v[62:63], v[170:171] op_sel_hi:[1,0]
	v_pk_mul_f32 v[166:167], v[28:29], v[170:171] op_sel_hi:[1,0]
	v_pk_mul_f32 v[168:169], v[30:31], v[170:171] op_sel_hi:[1,0]
	v_exp_f32_e32 v162, v162
	v_exp_f32_e32 v163, v163
	v_exp_f32_e32 v164, v164
	v_exp_f32_e32 v165, v165
	v_exp_f32_e32 v166, v166
	v_exp_f32_e32 v167, v167
	v_exp_f32_e32 v168, v168
	v_exp_f32_e32 v169, v169
	v_pk_add_f32 v[162:163], v[162:163], v[172:173] op_sel_hi:[1,0]
	v_pk_add_f32 v[164:165], v[164:165], v[172:173] op_sel_hi:[1,0]
	v_pk_add_f32 v[166:167], v[166:167], v[172:173] op_sel_hi:[1,0]
	v_pk_add_f32 v[168:169], v[168:169], v[172:173] op_sel_hi:[1,0]
	v_rcp_f32_e32 v162, v162
	v_rcp_f32_e32 v163, v163
	v_rcp_f32_e32 v164, v164
	v_rcp_f32_e32 v165, v165
	v_rcp_f32_e32 v166, v166
	v_rcp_f32_e32 v167, v167
	v_rcp_f32_e32 v168, v168
	v_rcp_f32_e32 v169, v169
	v_pk_mul_f32 v[162:163], v[60:61], v[162:163]
	v_pk_mul_f32 v[164:165], v[62:63], v[164:165]
	v_pk_mul_f32 v[166:167], v[28:29], v[166:167]
	v_pk_mul_f32 v[168:169], v[30:31], v[168:169]
; __device__ __forceinline__ unsigned cvt_pk_bf16(float lo, float hi) { unsigned r; asm volatile("v_cvt_pk_bf16_f32 %0, %1, %2" : "=v"(r) : "v"(lo), "v"(hi)); return r; }
;     __device__ __forceinline__ void operator()(AccRef acc, const Unit& u, int wr, int wc, int fr, int fq) const {
;     ...
;             for (int m = 0; m < 4; ++m) { const size_t row = (size_t)u.pm * 256 + ai * 128 + wr * 64 + m * 16 + fr; float o[8];
; #pragma unroll
;                 for (int bj = 0; bj < 2; ++bj) { const f32x4 gg = acc[ai][bj][m][0], uu = acc[ai][bj][m][1];
; #pragma unroll
;                     for (int j = 0; j < 4; ++j) o[4 * bj + j] = gg[j] * __builtin_amdgcn_rcpf(1.0f + __expf(-gg[j])) * uu[j]; }
;                 u32x4 w; w.x = cvt_pk_bf16(o[0], o[1]); w.y = cvt_pk_bf16(o[2], o[3]); w.z = cvt_pk_bf16(o[4], o[5]); w.w = cvt_pk_bf16(o[6], o[7]);
;                 *(u32x4*)(act + row * FF_ + (u.pn * 4 + wc) * 32 + 8 * fq) = w; }
	v_pk_mul_f32 v[162:163], v[56:57], v[162:163]
	v_pk_mul_f32 v[164:165], v[58:59], v[164:165]
	v_pk_mul_f32 v[166:167], v[24:25], v[166:167]
	v_pk_mul_f32 v[168:169], v[26:27], v[168:169]
	v_cvt_pk_bf16_f32 v150, v162, v163
	v_cvt_pk_bf16_f32 v151, v164, v165
	v_cvt_pk_bf16_f32 v152, v166, v167
	v_cvt_pk_bf16_f32 v153, v168, v169
	global_store_dwordx4 v[146:147], v[150:153], off
	s_mov_b32 s9, 0x18c000
	v_add_co_u32_e32 v146, vcc, s9, v144
	s_nop 0
	v_addc_co_u32_e32 v147, vcc, 0, v145, vcc
	v_pk_mul_f32 v[162:163], v[52:53], v[170:171] op_sel_hi:[1,0]
	v_pk_mul_f32 v[164:165], v[54:55], v[170:171] op_sel_hi:[1,0]
	v_pk_mul_f32 v[166:167], v[20:21], v[170:171] op_sel_hi:[1,0]
	v_pk_mul_f32 v[168:169], v[22:23], v[170:171] op_sel_hi:[1,0]
	v_exp_f32_e32 v162, v162
	v_exp_f32_e32 v163, v163
	v_exp_f32_e32 v164, v164
	v_exp_f32_e32 v165, v165
	v_exp_f32_e32 v166, v166
	v_exp_f32_e32 v167, v167
	v_exp_f32_e32 v168, v168
	v_exp_f32_e32 v169, v169
	v_pk_add_f32 v[162:163], v[162:163], v[172:173] op_sel_hi:[1,0]
	v_pk_add_f32 v[164:165], v[164:165], v[172:173] op_sel_hi:[1,0]
	v_pk_add_f32 v[166:167], v[166:167], v[172:173] op_sel_hi:[1,0]
	v_pk_add_f32 v[168:169], v[168:169], v[172:173] op_sel_hi:[1,0]
	v_rcp_f32_e32 v162, v162
	v_rcp_f32_e32 v163, v163
	v_rcp_f32_e32 v164, v164
	v_rcp_f32_e32 v165, v165
	v_rcp_f32_e32 v166, v166
	v_rcp_f32_e32 v167, v167
	v_rcp_f32_e32 v168, v168
	v_rcp_f32_e32 v169, v169
	v_pk_mul_f32 v[162:163], v[52:53], v[162:163]
	v_pk_mul_f32 v[164:165], v[54:55], v[164:165]
	v_pk_mul_f32 v[166:167], v[20:21], v[166:167]
	v_pk_mul_f32 v[168:169], v[22:23], v[168:169]
	v_pk_mul_f32 v[162:163], v[48:49], v[162:163]
	v_pk_mul_f32 v[164:165], v[50:51], v[164:165]
	v_pk_mul_f32 v[166:167], v[16:17], v[166:167]
	v_pk_mul_f32 v[168:169], v[18:19], v[168:169]
	v_cvt_pk_bf16_f32 v150, v162, v163
	v_cvt_pk_bf16_f32 v151, v164, v165
	v_cvt_pk_bf16_f32 v152, v166, v167
	v_cvt_pk_bf16_f32 v153, v168, v169
	global_store_dwordx4 v[146:147], v[150:153], off
	v_add_co_u32_e32 v146, vcc, s65, v144
	s_nop 0
	v_addc_co_u32_e32 v147, vcc, 0, v145, vcc
	v_pk_mul_f32 v[162:163], v[44:45], v[170:171] op_sel_hi:[1,0]
	v_pk_mul_f32 v[164:165], v[46:47], v[170:171] op_sel_hi:[1,0]
	v_pk_mul_f32 v[166:167], v[12:13], v[170:171] op_sel_hi:[1,0]
	v_pk_mul_f32 v[168:169], v[14:15], v[170:171] op_sel_hi:[1,0]
	v_exp_f32_e32 v162, v162
	v_exp_f32_e32 v163, v163
	v_exp_f32_e32 v164, v164
	v_exp_f32_e32 v165, v165
	v_exp_f32_e32 v166, v166
	v_exp_f32_e32 v167, v167
	v_exp_f32_e32 v168, v168
	v_exp_f32_e32 v169, v169
	v_pk_add_f32 v[162:163], v[162:163], v[172:173] op_sel_hi:[1,0]
	v_pk_add_f32 v[164:165], v[164:165], v[172:173] op_sel_hi:[1,0]
	v_pk_add_f32 v[166:167], v[166:167], v[172:173] op_sel_hi:[1,0]
	v_pk_add_f32 v[168:169], v[168:169], v[172:173] op_sel_hi:[1,0]
	v_rcp_f32_e32 v162, v162
	v_rcp_f32_e32 v163, v163
	v_rcp_f32_e32 v164, v164
	v_rcp_f32_e32 v165, v165
	v_rcp_f32_e32 v166, v166
	v_rcp_f32_e32 v167, v167
	v_rcp_f32_e32 v168, v168
	v_rcp_f32_e32 v169, v169
	v_pk_mul_f32 v[162:163], v[44:45], v[162:163]
	v_pk_mul_f32 v[164:165], v[46:47], v[164:165]
	v_pk_mul_f32 v[166:167], v[12:13], v[166:167]
	v_pk_mul_f32 v[168:169], v[14:15], v[168:169]
	v_pk_mul_f32 v[162:163], v[40:41], v[162:163]
	v_pk_mul_f32 v[164:165], v[42:43], v[164:165]
	v_pk_mul_f32 v[166:167], v[8:9], v[166:167]
	v_pk_mul_f32 v[168:169], v[10:11], v[168:169]
	v_cvt_pk_bf16_f32 v150, v162, v163
	v_cvt_pk_bf16_f32 v151, v164, v165
	v_cvt_pk_bf16_f32 v152, v166, v167
	v_cvt_pk_bf16_f32 v153, v168, v169
	global_store_dwordx4 v[146:147], v[150:153], off
	v_add_co_u32_e32 v144, vcc, 0x1e4000, v144
	v_addc_co_u32_e32 v145, vcc, 0, v145, vcc
	s_andn2_b64 vcc, exec, s[6:7]
	v_pk_mul_f32 v[162:163], v[36:37], v[170:171] op_sel_hi:[1,0]
	v_pk_mul_f32 v[164:165], v[38:39], v[170:171] op_sel_hi:[1,0]
	v_pk_mul_f32 v[166:167], v[4:5], v[170:171] op_sel_hi:[1,0]
	v_pk_mul_f32 v[168:169], v[6:7], v[170:171] op_sel_hi:[1,0]
	v_exp_f32_e32 v162, v162
	v_exp_f32_e32 v163, v163
	v_exp_f32_e32 v164, v164
	v_exp_f32_e32 v165, v165
	v_exp_f32_e32 v166, v166
	v_exp_f32_e32 v167, v167
	v_exp_f32_e32 v168, v168
	v_exp_f32_e32 v169, v169
	v_pk_add_f32 v[162:163], v[162:163], v[172:173] op_sel_hi:[1,0]
	v_pk_add_f32 v[164:165], v[164:165], v[172:173] op_sel_hi:[1,0]
	v_pk_add_f32 v[166:167], v[166:167], v[172:173] op_sel_hi:[1,0]
	v_pk_add_f32 v[168:169], v[168:169], v[172:173] op_sel_hi:[1,0]
	v_rcp_f32_e32 v162, v162
	v_rcp_f32_e32 v163, v163
	v_rcp_f32_e32 v164, v164
	v_rcp_f32_e32 v165, v165
	v_rcp_f32_e32 v166, v166
	v_rcp_f32_e32 v167, v167
	v_rcp_f32_e32 v168, v168
	v_rcp_f32_e32 v169, v169
	v_pk_mul_f32 v[162:163], v[36:37], v[162:163]
	v_pk_mul_f32 v[164:165], v[38:39], v[164:165]
	v_pk_mul_f32 v[166:167], v[4:5], v[166:167]
	v_pk_mul_f32 v[168:169], v[6:7], v[168:169]
	v_pk_mul_f32 v[162:163], v[32:33], v[162:163]
	v_pk_mul_f32 v[164:165], v[34:35], v[164:165]
	v_pk_mul_f32 v[166:167], v[0:1], v[166:167]
	v_pk_mul_f32 v[168:169], v[2:3], v[168:169]
	v_cvt_pk_bf16_f32 v150, v162, v163
	v_cvt_pk_bf16_f32 v151, v164, v165
	v_cvt_pk_bf16_f32 v152, v166, v167
	v_cvt_pk_bf16_f32 v153, v168, v169
	global_store_dwordx4 v[144:145], v[150:153], off
	s_cbranch_vccz .LBB0_173
	s_mov_b64 s[20:21], s[24:25]
	s_andn2_b64 vcc, exec, s[4:5]
	s_mov_b64 s[24:25], s[20:21]
	s_cbranch_vccnz .LBB0_174

; #define PG8_STAGE(bufoff, gbase, voff) do { _Pragma("unroll") for (int _i = 0; _i < 2; ++_i) \
;         __builtin_amdgcn_global_load_lds((const unsigned*)((const char*)(gbase) + (voff)[_i]), (LAS unsigned*)(lds + (bufoff) + ldsw + _i * 8192), 16, 0, 0); } while (0)
; #define PG8_LDA(dst, b, h) do { _Pragma("unroll") for (int m = 0; m < 4; ++m) _Pragma("unroll") for (int k = 0; k < 2; ++k) dst[m][k] = *(const LAS bf16x8*)(lds + PG8_SA(b, h) + aoff + m * 2048 + k * 1024); } while (0)
; #define PG8_LDB(dst, b, h) do { _Pragma("unroll") for (int n = 0; n < 2; ++n) _Pragma("unroll") for (int k = 0; k < 2; ++k) dst[n][k] = *(const LAS bf16x8*)(lds + PG8_SB(b, h) + boff + n * 2048 + k * 1024); } while (0)
; #define PG8_MMA(ai, bj, At, Bt) do { __builtin_amdgcn_s_setprio(1); _Pragma("unroll") for (int m = 0; m < 4; ++m) _Pragma("unroll") for (int n = 0; n < 2; ++n) _Pragma("unroll") for (int k = 0; k < 2; ++k) \
;         acc[ai][bj][m][n] = __builtin_amdgcn_mfma_f32_16x16x32_bf16(Bt[n][k], At[m][k], acc[ai][bj][m][n], 0, 0, 0); __builtin_amdgcn_s_setprio(0); } while (0)
; #define PG8_WAIT_L(n) asm volatile("s_waitcnt lgkmcnt(" #n ")" ::: "memory")
; #define PG8_BAR __builtin_amdgcn_s_barrier()
; #define PG8_SCHED __builtin_amdgcn_sched_barrier(0)
; template <class Epi>
; __device__ __forceinline__ void gemm_phase(LAS unsigned char* lds, const Gemm g, const Sched& S, const Epi& E) {
;     ...
;             PG8_LDB(B0, 0, 0); PG8_SCHED; PG8_LDA(At, 0, 0); PG8_STAGE(PG8_SA(1, 1), a1 + hstepA, voffA);
;             PG8_WAIT_L(8); PG8_BAR; PG8_WAIT_L(0); PG8_MMA(0, 0, At, B0); PG8_BAR; PG8_SCHED;
;             PG8_LDB(B1, 0, 1); PG8_STAGE(PG8_SB(0, 0), b2, voffB);
;             PG8_BAR; PG8_WAIT_L(0); PG8_MMA(0, 1, At, B1); PG8_BAR;
;             PG8_LDA(At, 0, 1); PG8_STAGE(PG8_SA(0, 0), a2, voffA);
;             PG8_BAR; PG8_WAIT_L(0); PG8_MMA(1, 0, At, B0); PG8_BAR; PG8_SCHED;
.LBB0_2088:
	v_add_u32_e32 v162, s62, v148
	s_add_u32 s38, s14, s36
	ds_read_b128 v[150:153], v162
	ds_read_b128 v[154:157], v162 offset:1024
	ds_read_b128 v[158:161], v162 offset:2048
	ds_read_b128 v[162:165], v162 offset:3072
	s_addc_u32 s39, s15, s37
	s_add_u32 s38, s38, 0x100
	s_addc_u32 s39, s39, 0
	s_add_u32 s82, s13, s36
	s_addc_u32 s83, s51, s37
	s_cmpk_eq_i32 s36, 0xf00
	s_cselect_b32 s55, s21, s39
	s_cselect_b32 s54, s79, s38
	s_cselect_b32 s39, s19, s83
	s_cselect_b32 s38, s80, s82
	v_lshl_add_u64 v[190:191], v[144:145], 0, s[36:37]
	s_add_i32 m0, s43, 0xc000
	ds_read_b128 v[166:169], v149
	ds_read_b128 v[170:173], v149 offset:1024
	ds_read_b128 v[174:177], v149 offset:2048
	ds_read_b128 v[178:181], v149 offset:3072
	ds_read_b128 v[182:185], v149 offset:4096
	ds_read_b128 v[186:189], v149 offset:5120
	ds_read_b128 v[194:197], v149 offset:6144
	ds_read_b128 v[198:201], v149 offset:7168
	global_load_lds_dwordx4 v[190:191], off
	v_lshl_add_u64 v[190:191], v[146:147], 0, s[36:37]
	s_add_i32 m0, s43, 0xe000
	s_nop 0
	global_load_lds_dwordx4 v[190:191], off
	s_waitcnt lgkmcnt(8)
	s_barrier
	s_waitcnt lgkmcnt(0)
	s_setprio 1
	s_waitcnt lgkmcnt(0)
	v_mfma_f32_16x16x32_bf16 v[124:127], v[150:153], v[166:169], v[124:127]
	v_mfma_f32_16x16x32_bf16 v[120:123], v[158:161], v[166:169], v[120:123]
	v_mfma_f32_16x16x32_bf16 v[116:119], v[150:153], v[174:177], v[116:119]
	v_mfma_f32_16x16x32_bf16 v[112:115], v[158:161], v[174:177], v[112:115]
	v_mfma_f32_16x16x32_bf16 v[108:111], v[150:153], v[182:185], v[108:111]
	v_mfma_f32_16x16x32_bf16 v[104:107], v[158:161], v[182:185], v[104:107]
	v_mfma_f32_16x16x32_bf16 v[100:103], v[150:153], v[194:197], v[100:103]
	v_mfma_f32_16x16x32_bf16 v[96:99], v[158:161], v[194:197], v[96:99]
	v_mfma_f32_16x16x32_bf16 v[124:127], v[154:157], v[170:173], v[124:127]
	v_mfma_f32_16x16x32_bf16 v[120:123], v[162:165], v[170:173], v[120:123]
	v_mfma_f32_16x16x32_bf16 v[116:119], v[154:157], v[178:181], v[116:119]
	v_mfma_f32_16x16x32_bf16 v[112:115], v[162:165], v[178:181], v[112:115]
	v_mfma_f32_16x16x32_bf16 v[108:111], v[154:157], v[186:189], v[108:111]
	v_mfma_f32_16x16x32_bf16 v[104:107], v[162:165], v[186:189], v[104:107]
	v_mfma_f32_16x16x32_bf16 v[100:103], v[154:157], v[198:201], v[100:103]
	v_mfma_f32_16x16x32_bf16 v[96:99], v[162:165], v[198:201], v[96:99]
	s_setprio 0
	s_barrier
	v_add_u32_e32 v190, s63, v148
	s_add_i32 s82, s62, s34
	ds_read_b128 v[202:205], v190
	ds_read_b128 v[206:209], v190 offset:1024
	ds_read_b128 v[210:213], v190 offset:2048
	ds_read_b128 v[214:217], v190 offset:3072
	v_lshl_add_u64 v[190:191], s[38:39], 0, v[130:131]
	s_mov_b32 m0, s82
	v_lshl_add_u64 v[218:219], s[38:39], 0, v[128:129]
	global_load_lds_dwordx4 v[190:191], off
	s_add_i32 m0, s82, 0x2000
	s_nop 0
	global_load_lds_dwordx4 v[218:219], off
	s_barrier
	s_waitcnt lgkmcnt(0)
	s_setprio 1
	s_waitcnt lgkmcnt(0)
	v_mfma_f32_16x16x32_bf16 v[92:95], v[202:205], v[166:169], v[92:95]
	v_mfma_f32_16x16x32_bf16 v[88:91], v[210:213], v[166:169], v[88:91]
	v_mfma_f32_16x16x32_bf16 v[84:87], v[202:205], v[174:177], v[84:87]
	v_mfma_f32_16x16x32_bf16 v[80:83], v[210:213], v[174:177], v[80:83]
	v_mfma_f32_16x16x32_bf16 v[76:79], v[202:205], v[182:185], v[76:79]
	v_mfma_f32_16x16x32_bf16 v[72:75], v[210:213], v[182:185], v[72:75]
	v_mfma_f32_16x16x32_bf16 v[68:71], v[202:205], v[194:197], v[68:71]
	v_mfma_f32_16x16x32_bf16 v[64:67], v[210:213], v[194:197], v[64:67]
	v_mfma_f32_16x16x32_bf16 v[92:95], v[206:209], v[170:173], v[92:95]
	v_mfma_f32_16x16x32_bf16 v[88:91], v[214:217], v[170:173], v[88:91]
	v_mfma_f32_16x16x32_bf16 v[84:87], v[206:209], v[178:181], v[84:87]
	v_mfma_f32_16x16x32_bf16 v[80:83], v[214:217], v[178:181], v[80:83]
	v_mfma_f32_16x16x32_bf16 v[76:79], v[206:209], v[186:189], v[76:79]
	v_mfma_f32_16x16x32_bf16 v[72:75], v[214:217], v[186:189], v[72:75]
	v_mfma_f32_16x16x32_bf16 v[68:71], v[206:209], v[198:201], v[68:71]
	v_mfma_f32_16x16x32_bf16 v[64:67], v[214:217], v[198:201], v[64:67]
	s_setprio 0
	s_mov_b32 m0, s43
	v_lshl_add_u64 v[220:221], s[54:55], 0, v[130:131]
	s_barrier
	ds_read_b128 v[166:169], v149 offset:16384
	ds_read_b128 v[170:173], v149 offset:17408
	ds_read_b128 v[174:177], v149 offset:18432
	ds_read_b128 v[178:181], v149 offset:19456
	ds_read_b128 v[182:185], v149 offset:20480
	ds_read_b128 v[186:189], v149 offset:21504
	ds_read_b128 v[194:197], v149 offset:22528
	ds_read_b128 v[198:201], v149 offset:23552
	global_load_lds_dwordx4 v[220:221], off
	v_lshl_add_u64 v[222:223], s[54:55], 0, v[128:129]
	s_mov_b32 m0, s52
	s_nop 0
	global_load_lds_dwordx4 v[222:223], off
	s_barrier
	s_waitcnt lgkmcnt(0)
	s_setprio 1
	s_waitcnt lgkmcnt(0)
	v_mfma_f32_16x16x32_bf16 v[60:63], v[150:153], v[166:169], v[60:63]
	v_mfma_f32_16x16x32_bf16 v[56:59], v[158:161], v[166:169], v[56:59]
	v_mfma_f32_16x16x32_bf16 v[52:55], v[150:153], v[174:177], v[52:55]
	v_mfma_f32_16x16x32_bf16 v[48:51], v[158:161], v[174:177], v[48:51]
	v_mfma_f32_16x16x32_bf16 v[44:47], v[150:153], v[182:185], v[44:47]
	v_mfma_f32_16x16x32_bf16 v[40:43], v[158:161], v[182:185], v[40:43]
	v_mfma_f32_16x16x32_bf16 v[36:39], v[150:153], v[194:197], v[36:39]
	v_mfma_f32_16x16x32_bf16 v[32:35], v[158:161], v[194:197], v[32:35]
	v_mfma_f32_16x16x32_bf16 v[60:63], v[154:157], v[170:173], v[60:63]
	v_mfma_f32_16x16x32_bf16 v[56:59], v[162:165], v[170:173], v[56:59]
	v_mfma_f32_16x16x32_bf16 v[52:55], v[154:157], v[178:181], v[52:55]
	v_mfma_f32_16x16x32_bf16 v[48:51], v[162:165], v[178:181], v[48:51]
	v_mfma_f32_16x16x32_bf16 v[44:47], v[154:157], v[186:189], v[44:47]
	v_mfma_f32_16x16x32_bf16 v[40:43], v[162:165], v[186:189], v[40:43]
	v_mfma_f32_16x16x32_bf16 v[36:39], v[154:157], v[198:201], v[36:39]
	v_mfma_f32_16x16x32_bf16 v[32:35], v[162:165], v[198:201], v[32:35]
	s_setprio 0
	s_barrier
; #define PG8_STAGE(bufoff, gbase, voff) do { _Pragma("unroll") for (int _i = 0; _i < 2; ++_i) \
;         __builtin_amdgcn_global_load_lds((const unsigned*)((const char*)(gbase) + (voff)[_i]), (LAS unsigned*)(lds + (bufoff) + ldsw + _i * 8192), 16, 0, 0); } while (0)
; #define PG8_LDA(dst, b, h) do { _Pragma("unroll") for (int m = 0; m < 4; ++m) _Pragma("unroll") for (int k = 0; k < 2; ++k) dst[m][k] = *(const LAS bf16x8*)(lds + PG8_SA(b, h) + aoff + m * 2048 + k * 1024); } while (0)
; #define PG8_LDB(dst, b, h) do { _Pragma("unroll") for (int n = 0; n < 2; ++n) _Pragma("unroll") for (int k = 0; k < 2; ++k) dst[n][k] = *(const LAS bf16x8*)(lds + PG8_SB(b, h) + boff + n * 2048 + k * 1024); } while (0)
; #define PG8_MMA(ai, bj, At, Bt) do { __builtin_amdgcn_s_setprio(1); _Pragma("unroll") for (int m = 0; m < 4; ++m) _Pragma("unroll") for (int n = 0; n < 2; ++n) _Pragma("unroll") for (int k = 0; k < 2; ++k) \
;         acc[ai][bj][m][n] = __builtin_amdgcn_mfma_f32_16x16x32_bf16(Bt[n][k], At[m][k], acc[ai][bj][m][n], 0, 0, 0); __builtin_amdgcn_s_setprio(0); } while (0)
; #define PG8_WAIT_V(n) asm volatile("s_waitcnt vmcnt(" #n ")" ::: "memory")
; #define PG8_WAIT_L(n) asm volatile("s_waitcnt lgkmcnt(" #n ")" ::: "memory")
; #define PG8_BAR __builtin_amdgcn_s_barrier()
; #define PG8_SCHED __builtin_amdgcn_sched_barrier(0)
; template <class Epi>
; __device__ __forceinline__ void gemm_phase(LAS unsigned char* lds, const Gemm g, const Sched& S, const Epi& E) {
;     ...
;             PG8_STAGE(PG8_SB(0, 1), b2 + hstepB, voffB);
;             PG8_WAIT_V(6); PG8_BAR; PG8_MMA(1, 1, At, B1); PG8_BAR;
;             PG8_LDB(B0, 1, 0); PG8_SCHED; PG8_LDA(At, 1, 0); PG8_STAGE(PG8_SA(0, 1), a2 + hstepA, voffA);
;             PG8_WAIT_L(8); PG8_BAR; PG8_WAIT_L(0); PG8_MMA(0, 0, At, B0); PG8_BAR; PG8_SCHED;
;             PG8_LDB(B1, 1, 1); PG8_STAGE(PG8_SB(1, 0), b3, voffB);
;             PG8_BAR; PG8_WAIT_L(0); PG8_MMA(0, 1, At, B1); PG8_BAR;
;             PG8_LDA(At, 1, 1); PG8_STAGE(PG8_SA(1, 0), a3, voffA);
;             PG8_BAR; PG8_WAIT_L(0); PG8_MMA(1, 0, At, B0); PG8_BAR; PG8_SCHED;
	s_add_u32 s82, s38, 0x80000
	s_addc_u32 s83, s39, 0
	s_add_i32 s84, s63, s34
	v_lshl_add_u64 v[150:151], s[82:83], 0, v[130:131]
	s_mov_b32 m0, s84
	s_nop 0
	global_load_lds_dwordx4 v[150:151], off
	v_lshl_add_u64 v[150:151], s[82:83], 0, v[128:129]
	s_add_i32 m0, s84, 0x2000
	s_nop 0
	global_load_lds_dwordx4 v[150:151], off
	s_waitcnt vmcnt(6)
	s_barrier
	s_setprio 1
	v_mfma_f32_16x16x32_bf16 v[28:31], v[202:205], v[166:169], v[28:31]
	v_mfma_f32_16x16x32_bf16 v[24:27], v[210:213], v[166:169], v[24:27]
	v_mfma_f32_16x16x32_bf16 v[20:23], v[202:205], v[174:177], v[20:23]
	v_mfma_f32_16x16x32_bf16 v[16:19], v[210:213], v[174:177], v[16:19]
	v_mfma_f32_16x16x32_bf16 v[12:15], v[202:205], v[182:185], v[12:15]
	v_mfma_f32_16x16x32_bf16 v[8:11], v[210:213], v[182:185], v[8:11]
	v_mfma_f32_16x16x32_bf16 v[4:7], v[202:205], v[194:197], v[4:7]
	v_mfma_f32_16x16x32_bf16 v[0:3], v[210:213], v[194:197], v[0:3]
	v_mfma_f32_16x16x32_bf16 v[28:31], v[206:209], v[170:173], v[28:31]
	v_mfma_f32_16x16x32_bf16 v[24:27], v[214:217], v[170:173], v[24:27]
	v_mfma_f32_16x16x32_bf16 v[20:23], v[206:209], v[178:181], v[20:23]
	v_mfma_f32_16x16x32_bf16 v[16:19], v[214:217], v[178:181], v[16:19]
	v_mfma_f32_16x16x32_bf16 v[12:15], v[206:209], v[186:189], v[12:15]
	v_mfma_f32_16x16x32_bf16 v[8:11], v[214:217], v[186:189], v[8:11]
	v_mfma_f32_16x16x32_bf16 v[4:7], v[206:209], v[198:201], v[4:7]
	v_mfma_f32_16x16x32_bf16 v[0:3], v[214:217], v[198:201], v[0:3]
	s_setprio 0
	s_add_i32 s82, 0, 0x18000
	v_add_u32_e32 v162, s82, v148
	s_barrier
	ds_read_b128 v[150:153], v162
	ds_read_b128 v[154:157], v162 offset:1024
	ds_read_b128 v[158:161], v162 offset:2048
	ds_read_b128 v[162:165], v162 offset:3072
	s_add_u32 s54, s54, 0x80000
	s_addc_u32 s55, s55, 0
	s_mov_b32 m0, s53
	v_lshl_add_u64 v[202:203], s[54:55], 0, v[130:131]
	ds_read_b128 v[166:169], v149 offset:32768
	ds_read_b128 v[170:173], v149 offset:33792
	ds_read_b128 v[174:177], v149 offset:34816
	ds_read_b128 v[178:181], v149 offset:35840
	ds_read_b128 v[182:185], v149 offset:36864
	ds_read_b128 v[186:189], v149 offset:37888
	ds_read_b128 v[194:197], v149 offset:38912
	ds_read_b128 v[198:201], v149 offset:39936
	global_load_lds_dwordx4 v[202:203], off
	v_lshl_add_u64 v[202:203], s[54:55], 0, v[128:129]
	s_mov_b32 m0, s56
	s_nop 0
	global_load_lds_dwordx4 v[202:203], off
	s_waitcnt lgkmcnt(8)
	s_barrier
	s_waitcnt lgkmcnt(0)
	s_setprio 1
	s_waitcnt lgkmcnt(0)
	v_mfma_f32_16x16x32_bf16 v[124:127], v[150:153], v[166:169], v[124:127]
	v_mfma_f32_16x16x32_bf16 v[120:123], v[158:161], v[166:169], v[120:123]
	v_mfma_f32_16x16x32_bf16 v[116:119], v[150:153], v[174:177], v[116:119]
	v_mfma_f32_16x16x32_bf16 v[112:115], v[158:161], v[174:177], v[112:115]
	v_mfma_f32_16x16x32_bf16 v[108:111], v[150:153], v[182:185], v[108:111]
	v_mfma_f32_16x16x32_bf16 v[104:107], v[158:161], v[182:185], v[104:107]
	v_mfma_f32_16x16x32_bf16 v[100:103], v[150:153], v[194:197], v[100:103]
	v_mfma_f32_16x16x32_bf16 v[96:99], v[158:161], v[194:197], v[96:99]
	v_mfma_f32_16x16x32_bf16 v[124:127], v[154:157], v[170:173], v[124:127]
	v_mfma_f32_16x16x32_bf16 v[120:123], v[162:165], v[170:173], v[120:123]
	v_mfma_f32_16x16x32_bf16 v[116:119], v[154:157], v[178:181], v[116:119]
	v_mfma_f32_16x16x32_bf16 v[112:115], v[162:165], v[178:181], v[112:115]
	v_mfma_f32_16x16x32_bf16 v[108:111], v[154:157], v[186:189], v[108:111]
	v_mfma_f32_16x16x32_bf16 v[104:107], v[162:165], v[186:189], v[104:107]
	v_mfma_f32_16x16x32_bf16 v[100:103], v[154:157], v[198:201], v[100:103]
	v_mfma_f32_16x16x32_bf16 v[96:99], v[162:165], v[198:201], v[96:99]
	s_setprio 0
	s_barrier
	s_add_i32 s54, 0, 0x1c000
	s_add_i32 s55, s82, s34
	v_add_u32_e32 v214, s54, v148
	v_lshl_add_u64 v[190:191], v[190:191], 0, s[16:17]
	s_mov_b32 m0, s55
	ds_read_b128 v[202:205], v214
	ds_read_b128 v[206:209], v214 offset:1024
	ds_read_b128 v[210:213], v214 offset:2048
	ds_read_b128 v[214:217], v214 offset:3072
	global_load_lds_dwordx4 v[190:191], off
	v_lshl_add_u64 v[190:191], v[218:219], 0, s[16:17]
	s_add_i32 m0, s55, 0x2000
	s_nop 0
	global_load_lds_dwordx4 v[190:191], off
	s_barrier
	s_waitcnt lgkmcnt(0)
	s_setprio 1
	s_waitcnt lgkmcnt(0)
	v_mfma_f32_16x16x32_bf16 v[92:95], v[202:205], v[166:169], v[92:95]
	v_mfma_f32_16x16x32_bf16 v[88:91], v[210:213], v[166:169], v[88:91]
	v_mfma_f32_16x16x32_bf16 v[84:87], v[202:205], v[174:177], v[84:87]
	v_mfma_f32_16x16x32_bf16 v[80:83], v[210:213], v[174:177], v[80:83]
	v_mfma_f32_16x16x32_bf16 v[76:79], v[202:205], v[182:185], v[76:79]
	v_mfma_f32_16x16x32_bf16 v[72:75], v[210:213], v[182:185], v[72:75]
	v_mfma_f32_16x16x32_bf16 v[68:71], v[202:205], v[194:197], v[68:71]
	v_mfma_f32_16x16x32_bf16 v[64:67], v[210:213], v[194:197], v[64:67]
	v_mfma_f32_16x16x32_bf16 v[92:95], v[206:209], v[170:173], v[92:95]
	v_mfma_f32_16x16x32_bf16 v[88:91], v[214:217], v[170:173], v[88:91]
	v_mfma_f32_16x16x32_bf16 v[84:87], v[206:209], v[178:181], v[84:87]
	v_mfma_f32_16x16x32_bf16 v[80:83], v[214:217], v[178:181], v[80:83]
	v_mfma_f32_16x16x32_bf16 v[76:79], v[206:209], v[186:189], v[76:79]
	v_mfma_f32_16x16x32_bf16 v[72:75], v[214:217], v[186:189], v[72:75]
	v_mfma_f32_16x16x32_bf16 v[68:71], v[206:209], v[198:201], v[68:71]
	v_mfma_f32_16x16x32_bf16 v[64:67], v[214:217], v[198:201], v[64:67]
	s_setprio 0
	s_mov_b32 m0, s60
	v_lshl_add_u64 v[190:191], v[220:221], 0, s[16:17]
	s_barrier
	ds_read_b128 v[166:169], v149 offset:49152
	ds_read_b128 v[170:173], v149 offset:50176
	ds_read_b128 v[174:177], v149 offset:51200
	ds_read_b128 v[178:181], v149 offset:52224
	ds_read_b128 v[182:185], v149 offset:53248
	ds_read_b128 v[186:189], v149 offset:54272
	ds_read_b128 v[194:197], v149 offset:55296
	ds_read_b128 v[198:201], v149 offset:56320
	global_load_lds_dwordx4 v[190:191], off
	v_lshl_add_u64 v[190:191], v[222:223], 0, s[16:17]
	s_mov_b32 m0, s61
	s_nop 0
	global_load_lds_dwordx4 v[190:191], off
	s_barrier
; __device__ __forceinline__ unsigned cvt_pk_bf16(float lo, float hi) { unsigned r; asm volatile("v_cvt_pk_bf16_f32 %0, %1, %2" : "=v"(r) : "v"(lo), "v"(hi)); return r; }
; #define PG8_STAGE(bufoff, gbase, voff) do { _Pragma("unroll") for (int _i = 0; _i < 2; ++_i) \
;         __builtin_amdgcn_global_load_lds((const unsigned*)((const char*)(gbase) + (voff)[_i]), (LAS unsigned*)(lds + (bufoff) + ldsw + _i * 8192), 16, 0, 0); } while (0)
; #define PG8_MMA(ai, bj, At, Bt) do { __builtin_amdgcn_s_setprio(1); _Pragma("unroll") for (int m = 0; m < 4; ++m) _Pragma("unroll") for (int n = 0; n < 2; ++n) _Pragma("unroll") for (int k = 0; k < 2; ++k) \
;         acc[ai][bj][m][n] = __builtin_amdgcn_mfma_f32_16x16x32_bf16(Bt[n][k], At[m][k], acc[ai][bj][m][n], 0, 0, 0); __builtin_amdgcn_s_setprio(0); } while (0)
; #define PG8_WAIT_V(n) asm volatile("s_waitcnt vmcnt(" #n ")" ::: "memory")
; #define PG8_BAR __builtin_amdgcn_s_barrier()
; template <class Epi>
; __device__ __forceinline__ void gemm_phase(LAS unsigned char* lds, const Gemm g, const Sched& S, const Epi& E) {
;     ...
;             PG8_STAGE(PG8_SB(1, 1), b3 + hstepB, voffB);
;             PG8_WAIT_V(6); PG8_BAR; PG8_MMA(1, 1, At, B1); PG8_BAR;
;     __device__ __forceinline__ void operator()(AccRef acc, const Unit& u, int wr, int wc, int fr, int fq) const {
;     ...
;             for (int m = 0; m < 4; ++m) { const size_t row = (size_t)u.pm * 256 + ai * 128 + wr * 64 + m * 16 + fr; float o[8];
; #pragma unroll
;                 for (int bj = 0; bj < 2; ++bj) { const f32x4 gg = acc[ai][bj][m][0], uu = acc[ai][bj][m][1];
; #pragma unroll
;                     for (int j = 0; j < 4; ++j) o[4 * bj + j] = gg[j] * __builtin_amdgcn_rcpf(1.0f + __expf(-gg[j])) * uu[j]; }
;                 u32x4 w; w.x = cvt_pk_bf16(o[0], o[1]); w.y = cvt_pk_bf16(o[2], o[3]); w.z = cvt_pk_bf16(o[4], o[5]); w.w = cvt_pk_bf16(o[6], o[7]);
;                 *(u32x4*)(act + row * FF_ + (u.pn * 4 + wc) * 32 + 8 * fq) = w; }
	s_waitcnt lgkmcnt(0)
	s_setprio 1
	s_waitcnt lgkmcnt(0)
	v_mfma_f32_16x16x32_bf16 v[60:63], v[150:153], v[166:169], v[60:63]
	v_mfma_f32_16x16x32_bf16 v[56:59], v[158:161], v[166:169], v[56:59]
	v_mfma_f32_16x16x32_bf16 v[52:55], v[150:153], v[174:177], v[52:55]
	v_mfma_f32_16x16x32_bf16 v[48:51], v[158:161], v[174:177], v[48:51]
	v_mfma_f32_16x16x32_bf16 v[44:47], v[150:153], v[182:185], v[44:47]
	v_mfma_f32_16x16x32_bf16 v[40:43], v[158:161], v[182:185], v[40:43]
	v_mfma_f32_16x16x32_bf16 v[36:39], v[150:153], v[194:197], v[36:39]
	v_mfma_f32_16x16x32_bf16 v[32:35], v[158:161], v[194:197], v[32:35]
	v_mfma_f32_16x16x32_bf16 v[60:63], v[154:157], v[170:173], v[60:63]
	v_mfma_f32_16x16x32_bf16 v[56:59], v[162:165], v[170:173], v[56:59]
	v_mfma_f32_16x16x32_bf16 v[52:55], v[154:157], v[178:181], v[52:55]
	v_mfma_f32_16x16x32_bf16 v[48:51], v[162:165], v[178:181], v[48:51]
	v_mfma_f32_16x16x32_bf16 v[44:47], v[154:157], v[186:189], v[44:47]
	v_mfma_f32_16x16x32_bf16 v[40:43], v[162:165], v[186:189], v[40:43]
	v_mfma_f32_16x16x32_bf16 v[36:39], v[154:157], v[198:201], v[36:39]
	v_mfma_f32_16x16x32_bf16 v[32:35], v[162:165], v[198:201], v[32:35]
	s_setprio 0
	s_barrier
	s_add_u32 s38, s38, 0x80080
	s_addc_u32 s39, s39, 0
	s_add_i32 s54, s54, s34
	v_lshl_add_u64 v[150:151], s[38:39], 0, v[130:131]
	s_mov_b32 m0, s54
	s_nop 0
	global_load_lds_dwordx4 v[150:151], off
	v_lshl_add_u64 v[150:151], s[38:39], 0, v[128:129]
	s_add_i32 m0, s54, 0x2000
	s_nop 0
	global_load_lds_dwordx4 v[150:151], off
	s_waitcnt vmcnt(6)
	s_barrier
	s_setprio 1
	v_mfma_f32_16x16x32_bf16 v[28:31], v[202:205], v[166:169], v[28:31]
	v_mfma_f32_16x16x32_bf16 v[24:27], v[210:213], v[166:169], v[24:27]
	v_mfma_f32_16x16x32_bf16 v[20:23], v[202:205], v[174:177], v[20:23]
	v_mfma_f32_16x16x32_bf16 v[16:19], v[210:213], v[174:177], v[16:19]
	v_mfma_f32_16x16x32_bf16 v[12:15], v[202:205], v[182:185], v[12:15]
	v_mfma_f32_16x16x32_bf16 v[8:11], v[210:213], v[182:185], v[8:11]
	v_mfma_f32_16x16x32_bf16 v[4:7], v[202:205], v[194:197], v[4:7]
	v_mfma_f32_16x16x32_bf16 v[0:3], v[210:213], v[194:197], v[0:3]
	v_mfma_f32_16x16x32_bf16 v[28:31], v[206:209], v[170:173], v[28:31]
	v_mfma_f32_16x16x32_bf16 v[24:27], v[214:217], v[170:173], v[24:27]
	v_mfma_f32_16x16x32_bf16 v[20:23], v[206:209], v[178:181], v[20:23]
	v_mfma_f32_16x16x32_bf16 v[16:19], v[214:217], v[178:181], v[16:19]
	v_mfma_f32_16x16x32_bf16 v[12:15], v[206:209], v[186:189], v[12:15]
	v_mfma_f32_16x16x32_bf16 v[8:11], v[214:217], v[186:189], v[8:11]
	v_mfma_f32_16x16x32_bf16 v[4:7], v[206:209], v[198:201], v[4:7]
	v_mfma_f32_16x16x32_bf16 v[0:3], v[214:217], v[198:201], v[0:3]
	s_setprio 0
	s_add_i32 s81, s81, 2
	s_add_u32 s36, s36, 0x100
	s_addc_u32 s37, s37, 0
	s_cmp_gt_u32 s81, 29
	s_barrier
	s_cbranch_scc0 .LBB0_2088
	v_mov_b32_e32 v170, 0xbfb8aa3b
	v_mov_b32_e32 v172, 1.0
	s_add_u32 s36, s13, 0xffffff00
	s_addc_u32 s37, s51, -1
	s_ashr_i32 s13, s12, 31
	s_lshl_b64 s[38:39], s[12:13], 8
	v_lshl_add_u64 v[144:145], v[134:135], 0, s[38:39]
	v_mov_b64_e32 v[146:147], s[44:45]
	v_mad_u64_u32 v[146:147], s[54:55], v144, s64, v[146:147]
	s_lshl_b32 s13, s58, 7
	v_mov_b32_e32 v144, v147
	s_or_b32 s38, s13, s59
	v_mad_u64_u32 v[144:145], s[54:55], v145, s64, v[144:145]
	s_ashr_i32 s39, s38, 31
	v_mov_b32_e32 v147, v144
	v_lshl_add_u64 v[144:145], s[38:39], 1, v[146:147]
	v_lshl_add_u64 v[144:145], v[144:145], 0, v[132:133]
	v_pk_mul_f32 v[162:163], v[124:125], v[170:171] op_sel_hi:[1,0]
	v_pk_mul_f32 v[164:165], v[126:127], v[170:171] op_sel_hi:[1,0]
	v_pk_mul_f32 v[166:167], v[92:93], v[170:171] op_sel_hi:[1,0]
	v_pk_mul_f32 v[168:169], v[94:95], v[170:171] op_sel_hi:[1,0]
	v_exp_f32_e32 v162, v162
	v_exp_f32_e32 v163, v163
	v_exp_f32_e32 v164, v164
	v_exp_f32_e32 v165, v165
	v_exp_f32_e32 v166, v166
	v_exp_f32_e32 v167, v167
	v_exp_f32_e32 v168, v168
	v_exp_f32_e32 v169, v169
	v_pk_add_f32 v[162:163], v[162:163], v[172:173] op_sel_hi:[1,0]
	v_pk_add_f32 v[164:165], v[164:165], v[172:173] op_sel_hi:[1,0]
	v_pk_add_f32 v[166:167], v[166:167], v[172:173] op_sel_hi:[1,0]
	v_pk_add_f32 v[168:169], v[168:169], v[172:173] op_sel_hi:[1,0]
	v_rcp_f32_e32 v162, v162
	v_rcp_f32_e32 v163, v163
	v_rcp_f32_e32 v164, v164
	v_rcp_f32_e32 v165, v165
	v_rcp_f32_e32 v166, v166
	v_rcp_f32_e32 v167, v167
	v_rcp_f32_e32 v168, v168
	v_rcp_f32_e32 v169, v169
	v_pk_mul_f32 v[162:163], v[124:125], v[162:163]
	v_pk_mul_f32 v[164:165], v[126:127], v[164:165]
	v_pk_mul_f32 v[166:167], v[92:93], v[166:167]
	v_pk_mul_f32 v[168:169], v[94:95], v[168:169]
	v_pk_mul_f32 v[162:163], v[120:121], v[162:163]
	v_pk_mul_f32 v[164:165], v[122:123], v[164:165]
	v_pk_mul_f32 v[166:167], v[88:89], v[166:167]
	v_pk_mul_f32 v[168:169], v[90:91], v[168:169]
	v_cvt_pk_bf16_f32 v150, v162, v163
	v_cvt_pk_bf16_f32 v151, v164, v165
	v_cvt_pk_bf16_f32 v152, v166, v167
	v_cvt_pk_bf16_f32 v153, v168, v169
	global_store_dwordx4 v[144:145], v[150:153], off
	v_add_co_u32_e32 v146, vcc, s65, v144
	s_nop 0
	v_addc_co_u32_e32 v147, vcc, 0, v145, vcc
	v_pk_mul_f32 v[162:163], v[116:117], v[170:171] op_sel_hi:[1,0]
	v_pk_mul_f32 v[164:165], v[118:119], v[170:171] op_sel_hi:[1,0]
	v_pk_mul_f32 v[166:167], v[84:85], v[170:171] op_sel_hi:[1,0]
	v_pk_mul_f32 v[168:169], v[86:87], v[170:171] op_sel_hi:[1,0]
	v_exp_f32_e32 v162, v162
	v_exp_f32_e32 v163, v163
	v_exp_f32_e32 v164, v164
	v_exp_f32_e32 v165, v165
	v_exp_f32_e32 v166, v166
	v_exp_f32_e32 v167, v167
	v_exp_f32_e32 v168, v168
	v_exp_f32_e32 v169, v169
	v_pk_add_f32 v[162:163], v[162:163], v[172:173] op_sel_hi:[1,0]
	v_pk_add_f32 v[164:165], v[164:165], v[172:173] op_sel_hi:[1,0]
	v_pk_add_f32 v[166:167], v[166:167], v[172:173] op_sel_hi:[1,0]
; __device__ __forceinline__ unsigned cvt_pk_bf16(float lo, float hi) { unsigned r; asm volatile("v_cvt_pk_bf16_f32 %0, %1, %2" : "=v"(r) : "v"(lo), "v"(hi)); return r; }
;     __device__ __forceinline__ void operator()(AccRef acc, const Unit& u, int wr, int wc, int fr, int fq) const {
;     ...
;         for (int ai = 0; ai < 2; ++ai)
; #pragma unroll
;             for (int m = 0; m < 4; ++m) { const size_t row = (size_t)u.pm * 256 + ai * 128 + wr * 64 + m * 16 + fr; float o[8];
; #pragma unroll
;                 for (int bj = 0; bj < 2; ++bj) { const f32x4 gg = acc[ai][bj][m][0], uu = acc[ai][bj][m][1];
; #pragma unroll
;                     for (int j = 0; j < 4; ++j) o[4 * bj + j] = gg[j] * __builtin_amdgcn_rcpf(1.0f + __expf(-gg[j])) * uu[j]; }
;                 u32x4 w; w.x = cvt_pk_bf16(o[0], o[1]); w.y = cvt_pk_bf16(o[2], o[3]); w.z = cvt_pk_bf16(o[4], o[5]); w.w = cvt_pk_bf16(o[6], o[7]);
;                 *(u32x4*)(act + row * FF_ + (u.pn * 4 + wc) * 32 + 8 * fq) = w; }
	v_pk_add_f32 v[168:169], v[168:169], v[172:173] op_sel_hi:[1,0]
	v_rcp_f32_e32 v162, v162
	v_rcp_f32_e32 v163, v163
	v_rcp_f32_e32 v164, v164
	v_rcp_f32_e32 v165, v165
	v_rcp_f32_e32 v166, v166
	v_rcp_f32_e32 v167, v167
	v_rcp_f32_e32 v168, v168
	v_rcp_f32_e32 v169, v169
	v_pk_mul_f32 v[162:163], v[116:117], v[162:163]
	v_pk_mul_f32 v[164:165], v[118:119], v[164:165]
	v_pk_mul_f32 v[166:167], v[84:85], v[166:167]
	v_pk_mul_f32 v[168:169], v[86:87], v[168:169]
	v_pk_mul_f32 v[162:163], v[112:113], v[162:163]
	v_pk_mul_f32 v[164:165], v[114:115], v[164:165]
	v_pk_mul_f32 v[166:167], v[80:81], v[166:167]
	v_pk_mul_f32 v[168:169], v[82:83], v[168:169]
	v_cvt_pk_bf16_f32 v150, v162, v163
	v_cvt_pk_bf16_f32 v151, v164, v165
	v_cvt_pk_bf16_f32 v152, v166, v167
	v_cvt_pk_bf16_f32 v153, v168, v169
	global_store_dwordx4 v[146:147], v[150:153], off
	v_add_co_u32_e32 v146, vcc, s66, v144
	s_nop 0
	v_addc_co_u32_e32 v147, vcc, 0, v145, vcc
	v_pk_mul_f32 v[162:163], v[108:109], v[170:171] op_sel_hi:[1,0]
	v_pk_mul_f32 v[164:165], v[110:111], v[170:171] op_sel_hi:[1,0]
	v_pk_mul_f32 v[166:167], v[76:77], v[170:171] op_sel_hi:[1,0]
	v_pk_mul_f32 v[168:169], v[78:79], v[170:171] op_sel_hi:[1,0]
	v_exp_f32_e32 v162, v162
	v_exp_f32_e32 v163, v163
	v_exp_f32_e32 v164, v164
	v_exp_f32_e32 v165, v165
	v_exp_f32_e32 v166, v166
	v_exp_f32_e32 v167, v167
	v_exp_f32_e32 v168, v168
	v_exp_f32_e32 v169, v169
	v_pk_add_f32 v[162:163], v[162:163], v[172:173] op_sel_hi:[1,0]
	v_pk_add_f32 v[164:165], v[164:165], v[172:173] op_sel_hi:[1,0]
	v_pk_add_f32 v[166:167], v[166:167], v[172:173] op_sel_hi:[1,0]
	v_pk_add_f32 v[168:169], v[168:169], v[172:173] op_sel_hi:[1,0]
	v_rcp_f32_e32 v162, v162
	v_rcp_f32_e32 v163, v163
	v_rcp_f32_e32 v164, v164
	v_rcp_f32_e32 v165, v165
	v_rcp_f32_e32 v166, v166
	v_rcp_f32_e32 v167, v167
	v_rcp_f32_e32 v168, v168
	v_rcp_f32_e32 v169, v169
	v_pk_mul_f32 v[162:163], v[108:109], v[162:163]
	v_pk_mul_f32 v[164:165], v[110:111], v[164:165]
	v_pk_mul_f32 v[166:167], v[76:77], v[166:167]
	v_pk_mul_f32 v[168:169], v[78:79], v[168:169]
	v_pk_mul_f32 v[162:163], v[104:105], v[162:163]
	v_pk_mul_f32 v[164:165], v[106:107], v[164:165]
	v_pk_mul_f32 v[166:167], v[72:73], v[166:167]
	v_pk_mul_f32 v[168:169], v[74:75], v[168:169]
	v_cvt_pk_bf16_f32 v150, v162, v163
	v_cvt_pk_bf16_f32 v151, v164, v165
	v_cvt_pk_bf16_f32 v152, v166, v167
	v_cvt_pk_bf16_f32 v153, v168, v169
	global_store_dwordx4 v[146:147], v[150:153], off
	v_add_co_u32_e32 v146, vcc, s67, v144
	s_nop 0
	v_addc_co_u32_e32 v147, vcc, 0, v145, vcc
	v_pk_mul_f32 v[162:163], v[100:101], v[170:171] op_sel_hi:[1,0]
	v_pk_mul_f32 v[164:165], v[102:103], v[170:171] op_sel_hi:[1,0]
	v_pk_mul_f32 v[166:167], v[68:69], v[170:171] op_sel_hi:[1,0]
	v_pk_mul_f32 v[168:169], v[70:71], v[170:171] op_sel_hi:[1,0]
	v_exp_f32_e32 v162, v162
	v_exp_f32_e32 v163, v163
	v_exp_f32_e32 v164, v164
	v_exp_f32_e32 v165, v165
	v_exp_f32_e32 v166, v166
	v_exp_f32_e32 v167, v167
	v_exp_f32_e32 v168, v168
	v_exp_f32_e32 v169, v169
	v_pk_add_f32 v[162:163], v[162:163], v[172:173] op_sel_hi:[1,0]
	v_pk_add_f32 v[164:165], v[164:165], v[172:173] op_sel_hi:[1,0]
	v_pk_add_f32 v[166:167], v[166:167], v[172:173] op_sel_hi:[1,0]
	v_pk_add_f32 v[168:169], v[168:169], v[172:173] op_sel_hi:[1,0]
	v_rcp_f32_e32 v162, v162
	v_rcp_f32_e32 v163, v163
	v_rcp_f32_e32 v164, v164
	v_rcp_f32_e32 v165, v165
	v_rcp_f32_e32 v166, v166
	v_rcp_f32_e32 v167, v167
	v_rcp_f32_e32 v168, v168
	v_rcp_f32_e32 v169, v169
	v_pk_mul_f32 v[162:163], v[100:101], v[162:163]
	v_pk_mul_f32 v[164:165], v[102:103], v[164:165]
	v_pk_mul_f32 v[166:167], v[68:69], v[166:167]
	v_pk_mul_f32 v[168:169], v[70:71], v[168:169]
	v_pk_mul_f32 v[162:163], v[96:97], v[162:163]
	v_pk_mul_f32 v[164:165], v[98:99], v[164:165]
	v_pk_mul_f32 v[166:167], v[64:65], v[166:167]
	v_pk_mul_f32 v[168:169], v[66:67], v[168:169]
	v_cvt_pk_bf16_f32 v150, v162, v163
	v_cvt_pk_bf16_f32 v151, v164, v165
	v_cvt_pk_bf16_f32 v152, v166, v167
	v_cvt_pk_bf16_f32 v153, v168, v169
	global_store_dwordx4 v[146:147], v[150:153], off
	v_add_co_u32_e32 v146, vcc, s70, v144
	s_nop 0
	v_addc_co_u32_e32 v147, vcc, 0, v145, vcc
	v_pk_mul_f32 v[162:163], v[60:61], v[170:171] op_sel_hi:[1,0]
	v_pk_mul_f32 v[164:165], v[62:63], v[170:171] op_sel_hi:[1,0]
	v_pk_mul_f32 v[166:167], v[28:29], v[170:171] op_sel_hi:[1,0]
	v_pk_mul_f32 v[168:169], v[30:31], v[170:171] op_sel_hi:[1,0]
	v_exp_f32_e32 v162, v162
	v_exp_f32_e32 v163, v163
	v_exp_f32_e32 v164, v164
	v_exp_f32_e32 v165, v165
	v_exp_f32_e32 v166, v166
	v_exp_f32_e32 v167, v167
	v_exp_f32_e32 v168, v168
	v_exp_f32_e32 v169, v169
	v_pk_add_f32 v[162:163], v[162:163], v[172:173] op_sel_hi:[1,0]
	v_pk_add_f32 v[164:165], v[164:165], v[172:173] op_sel_hi:[1,0]
	v_pk_add_f32 v[166:167], v[166:167], v[172:173] op_sel_hi:[1,0]
	v_pk_add_f32 v[168:169], v[168:169], v[172:173] op_sel_hi:[1,0]
	v_rcp_f32_e32 v162, v162
	v_rcp_f32_e32 v163, v163
	v_rcp_f32_e32 v164, v164
	v_rcp_f32_e32 v165, v165
	v_rcp_f32_e32 v166, v166
	v_rcp_f32_e32 v167, v167
	v_rcp_f32_e32 v168, v168
	v_rcp_f32_e32 v169, v169
	v_pk_mul_f32 v[162:163], v[60:61], v[162:163]
	v_pk_mul_f32 v[164:165], v[62:63], v[164:165]
	v_pk_mul_f32 v[166:167], v[28:29], v[166:167]
	v_pk_mul_f32 v[168:169], v[30:31], v[168:169]
	v_pk_mul_f32 v[162:163], v[56:57], v[162:163]
; __device__ __forceinline__ unsigned cvt_pk_bf16(float lo, float hi) { unsigned r; asm volatile("v_cvt_pk_bf16_f32 %0, %1, %2" : "=v"(r) : "v"(lo), "v"(hi)); return r; }
;     __device__ __forceinline__ void operator()(AccRef acc, const Unit& u, int wr, int wc, int fr, int fq) const {
;     ...
;         for (int ai = 0; ai < 2; ++ai)
; #pragma unroll
;             for (int m = 0; m < 4; ++m) { const size_t row = (size_t)u.pm * 256 + ai * 128 + wr * 64 + m * 16 + fr; float o[8];
; #pragma unroll
;                 for (int bj = 0; bj < 2; ++bj) { const f32x4 gg = acc[ai][bj][m][0], uu = acc[ai][bj][m][1];
; #pragma unroll
;                     for (int j = 0; j < 4; ++j) o[4 * bj + j] = gg[j] * __builtin_amdgcn_rcpf(1.0f + __expf(-gg[j])) * uu[j]; }
;                 u32x4 w; w.x = cvt_pk_bf16(o[0], o[1]); w.y = cvt_pk_bf16(o[2], o[3]); w.z = cvt_pk_bf16(o[4], o[5]); w.w = cvt_pk_bf16(o[6], o[7]);
;                 *(u32x4*)(act + row * FF_ + (u.pn * 4 + wc) * 32 + 8 * fq) = w; }
	v_pk_mul_f32 v[164:165], v[58:59], v[164:165]
	v_pk_mul_f32 v[166:167], v[24:25], v[166:167]
	v_pk_mul_f32 v[168:169], v[26:27], v[168:169]
	v_cvt_pk_bf16_f32 v150, v162, v163
	v_cvt_pk_bf16_f32 v151, v164, v165
	v_cvt_pk_bf16_f32 v152, v166, v167
	v_cvt_pk_bf16_f32 v153, v168, v169
	global_store_dwordx4 v[146:147], v[150:153], off
	v_add_co_u32_e32 v146, vcc, s71, v144
	s_nop 0
	v_addc_co_u32_e32 v147, vcc, 0, v145, vcc
	v_pk_mul_f32 v[162:163], v[52:53], v[170:171] op_sel_hi:[1,0]
	v_pk_mul_f32 v[164:165], v[54:55], v[170:171] op_sel_hi:[1,0]
	v_pk_mul_f32 v[166:167], v[20:21], v[170:171] op_sel_hi:[1,0]
	v_pk_mul_f32 v[168:169], v[22:23], v[170:171] op_sel_hi:[1,0]
	v_exp_f32_e32 v162, v162
	v_exp_f32_e32 v163, v163
	v_exp_f32_e32 v164, v164
	v_exp_f32_e32 v165, v165
	v_exp_f32_e32 v166, v166
	v_exp_f32_e32 v167, v167
	v_exp_f32_e32 v168, v168
	v_exp_f32_e32 v169, v169
	v_pk_add_f32 v[162:163], v[162:163], v[172:173] op_sel_hi:[1,0]
	v_pk_add_f32 v[164:165], v[164:165], v[172:173] op_sel_hi:[1,0]
	v_pk_add_f32 v[166:167], v[166:167], v[172:173] op_sel_hi:[1,0]
	v_pk_add_f32 v[168:169], v[168:169], v[172:173] op_sel_hi:[1,0]
	v_rcp_f32_e32 v162, v162
	v_rcp_f32_e32 v163, v163
	v_rcp_f32_e32 v164, v164
	v_rcp_f32_e32 v165, v165
	v_rcp_f32_e32 v166, v166
	v_rcp_f32_e32 v167, v167
	v_rcp_f32_e32 v168, v168
	v_rcp_f32_e32 v169, v169
	v_pk_mul_f32 v[162:163], v[52:53], v[162:163]
	v_pk_mul_f32 v[164:165], v[54:55], v[164:165]
	v_pk_mul_f32 v[166:167], v[20:21], v[166:167]
	v_pk_mul_f32 v[168:169], v[22:23], v[168:169]
	v_pk_mul_f32 v[162:163], v[48:49], v[162:163]
	v_pk_mul_f32 v[164:165], v[50:51], v[164:165]
	v_pk_mul_f32 v[166:167], v[16:17], v[166:167]
	v_pk_mul_f32 v[168:169], v[18:19], v[168:169]
	v_cvt_pk_bf16_f32 v150, v162, v163
	v_cvt_pk_bf16_f32 v151, v164, v165
	v_cvt_pk_bf16_f32 v152, v166, v167
	v_cvt_pk_bf16_f32 v153, v168, v169
	global_store_dwordx4 v[146:147], v[150:153], off
	v_add_co_u32_e32 v146, vcc, s78, v144
	s_nop 0
	v_addc_co_u32_e32 v147, vcc, 0, v145, vcc
	v_pk_mul_f32 v[162:163], v[44:45], v[170:171] op_sel_hi:[1,0]
	v_pk_mul_f32 v[164:165], v[46:47], v[170:171] op_sel_hi:[1,0]
	v_pk_mul_f32 v[166:167], v[12:13], v[170:171] op_sel_hi:[1,0]
	v_pk_mul_f32 v[168:169], v[14:15], v[170:171] op_sel_hi:[1,0]
	v_exp_f32_e32 v162, v162
	v_exp_f32_e32 v163, v163
	v_exp_f32_e32 v164, v164
	v_exp_f32_e32 v165, v165
	v_exp_f32_e32 v166, v166
	v_exp_f32_e32 v167, v167
	v_exp_f32_e32 v168, v168
	v_exp_f32_e32 v169, v169
	v_pk_add_f32 v[162:163], v[162:163], v[172:173] op_sel_hi:[1,0]
	v_pk_add_f32 v[164:165], v[164:165], v[172:173] op_sel_hi:[1,0]
	v_pk_add_f32 v[166:167], v[166:167], v[172:173] op_sel_hi:[1,0]
	v_pk_add_f32 v[168:169], v[168:169], v[172:173] op_sel_hi:[1,0]
	v_rcp_f32_e32 v162, v162
	v_rcp_f32_e32 v163, v163
	v_rcp_f32_e32 v164, v164
	v_rcp_f32_e32 v165, v165
	v_rcp_f32_e32 v166, v166
	v_rcp_f32_e32 v167, v167
	v_rcp_f32_e32 v168, v168
	v_rcp_f32_e32 v169, v169
	v_pk_mul_f32 v[162:163], v[44:45], v[162:163]
	v_pk_mul_f32 v[164:165], v[46:47], v[164:165]
	v_pk_mul_f32 v[166:167], v[12:13], v[166:167]
	v_pk_mul_f32 v[168:169], v[14:15], v[168:169]
	v_pk_mul_f32 v[162:163], v[40:41], v[162:163]
	v_pk_mul_f32 v[164:165], v[42:43], v[164:165]
	v_pk_mul_f32 v[166:167], v[8:9], v[166:167]
	v_pk_mul_f32 v[168:169], v[10:11], v[168:169]
	v_cvt_pk_bf16_f32 v150, v162, v163
	v_cvt_pk_bf16_f32 v151, v164, v165
	v_cvt_pk_bf16_f32 v152, v166, v167
	v_cvt_pk_bf16_f32 v153, v168, v169
	global_store_dwordx4 v[146:147], v[150:153], off
	v_add_co_u32_e32 v144, vcc, 0x1e4000, v144
	v_addc_co_u32_e32 v145, vcc, 0, v145, vcc
	s_andn2_b64 vcc, exec, s[10:11]
	v_pk_mul_f32 v[162:163], v[36:37], v[170:171] op_sel_hi:[1,0]
	v_pk_mul_f32 v[164:165], v[38:39], v[170:171] op_sel_hi:[1,0]
	v_pk_mul_f32 v[166:167], v[4:5], v[170:171] op_sel_hi:[1,0]
	v_pk_mul_f32 v[168:169], v[6:7], v[170:171] op_sel_hi:[1,0]
	v_exp_f32_e32 v162, v162
	v_exp_f32_e32 v163, v163
	v_exp_f32_e32 v164, v164
	v_exp_f32_e32 v165, v165
	v_exp_f32_e32 v166, v166
	v_exp_f32_e32 v167, v167
	v_exp_f32_e32 v168, v168
	v_exp_f32_e32 v169, v169
	v_pk_add_f32 v[162:163], v[162:163], v[172:173] op_sel_hi:[1,0]
	v_pk_add_f32 v[164:165], v[164:165], v[172:173] op_sel_hi:[1,0]
	v_pk_add_f32 v[166:167], v[166:167], v[172:173] op_sel_hi:[1,0]
	v_pk_add_f32 v[168:169], v[168:169], v[172:173] op_sel_hi:[1,0]
	v_rcp_f32_e32 v162, v162
	v_rcp_f32_e32 v163, v163
	v_rcp_f32_e32 v164, v164
	v_rcp_f32_e32 v165, v165
	v_rcp_f32_e32 v166, v166
	v_rcp_f32_e32 v167, v167
	v_rcp_f32_e32 v168, v168
	v_rcp_f32_e32 v169, v169
	v_pk_mul_f32 v[162:163], v[36:37], v[162:163]
	v_pk_mul_f32 v[164:165], v[38:39], v[164:165]
	v_pk_mul_f32 v[166:167], v[4:5], v[166:167]
	v_pk_mul_f32 v[168:169], v[6:7], v[168:169]
	v_pk_mul_f32 v[162:163], v[32:33], v[162:163]
	v_pk_mul_f32 v[164:165], v[34:35], v[164:165]
	v_pk_mul_f32 v[166:167], v[0:1], v[166:167]
	v_pk_mul_f32 v[168:169], v[2:3], v[168:169]
	v_cvt_pk_bf16_f32 v150, v162, v163
	v_cvt_pk_bf16_f32 v151, v164, v165
	v_cvt_pk_bf16_f32 v152, v166, v167
	v_cvt_pk_bf16_f32 v153, v168, v169
	global_store_dwordx4 v[144:145], v[150:153], off
	s_cbranch_vccz .LBB0_2084
	s_mov_b64 s[22:23], s[36:37]
	s_andn2_b64 vcc, exec, s[8:9]
	s_mov_b64 s[36:37], s[22:23]
	s_cbranch_vccnz .LBB0_2085

; #define PG8_STAGE(bufoff, gbase, voff) do { _Pragma("unroll") for (int _i = 0; _i < 2; ++_i) \
;         __builtin_amdgcn_global_load_lds((const unsigned*)((const char*)(gbase) + (voff)[_i]), (LAS unsigned*)(lds + (bufoff) + ldsw + _i * 8192), 16, 0, 0); } while (0)
; #define PG8_LDA(dst, b, h) do { _Pragma("unroll") for (int m = 0; m < 4; ++m) _Pragma("unroll") for (int k = 0; k < 2; ++k) dst[m][k] = *(const LAS bf16x8*)(lds + PG8_SA(b, h) + aoff + m * 2048 + k * 1024); } while (0)
; #define PG8_LDB(dst, b, h) do { _Pragma("unroll") for (int n = 0; n < 2; ++n) _Pragma("unroll") for (int k = 0; k < 2; ++k) dst[n][k] = *(const LAS bf16x8*)(lds + PG8_SB(b, h) + boff + n * 2048 + k * 1024); } while (0)
; #define PG8_MMA(ai, bj, At, Bt) do { __builtin_amdgcn_s_setprio(1); _Pragma("unroll") for (int m = 0; m < 4; ++m) _Pragma("unroll") for (int n = 0; n < 2; ++n) _Pragma("unroll") for (int k = 0; k < 2; ++k) \
;         acc[ai][bj][m][n] = __builtin_amdgcn_mfma_f32_16x16x32_bf16(Bt[n][k], At[m][k], acc[ai][bj][m][n], 0, 0, 0); __builtin_amdgcn_s_setprio(0); } while (0)
; #define PG8_WAIT_V(n) asm volatile("s_waitcnt vmcnt(" #n ")" ::: "memory")
; #define PG8_WAIT_L(n) asm volatile("s_waitcnt lgkmcnt(" #n ")" ::: "memory")
; #define PG8_BAR __builtin_amdgcn_s_barrier()
; #define PG8_SCHED __builtin_amdgcn_sched_barrier(0)
; template <class Epi>
; __device__ __forceinline__ void gemm_phase(LAS unsigned char* lds, const Gemm g, const Sched& S, const Epi& E) {
;     ...
;             PG8_LDB(B0, 0, 0); PG8_SCHED; PG8_LDA(At, 0, 0); PG8_STAGE(PG8_SA(1, 1), a1 + hstepA, voffA);
;             PG8_WAIT_L(8); PG8_BAR; PG8_WAIT_L(0); PG8_MMA(0, 0, At, B0); PG8_BAR; PG8_SCHED;
;             PG8_LDB(B1, 0, 1); PG8_STAGE(PG8_SB(0, 0), b2, voffB);
;             PG8_BAR; PG8_WAIT_L(0); PG8_MMA(0, 1, At, B1); PG8_BAR;
;             PG8_LDA(At, 0, 1); PG8_STAGE(PG8_SA(0, 0), a2, voffA);
;             PG8_BAR; PG8_WAIT_L(0); PG8_MMA(1, 0, At, B0); PG8_BAR; PG8_SCHED;
;             PG8_STAGE(PG8_SB(0, 1), b2 + hstepB, voffB);
;             PG8_WAIT_V(6); PG8_BAR; PG8_MMA(1, 1, At, B1); PG8_BAR;
.LBB0_3085:
	v_add_u32_e32 v162, s54, v148
	s_add_u32 s36, s12, s24
	ds_read_b128 v[150:153], v162
	ds_read_b128 v[154:157], v162 offset:1024
	ds_read_b128 v[158:161], v162 offset:2048
	ds_read_b128 v[162:165], v162 offset:3072
	s_addc_u32 s37, s13, s25
	s_add_u32 s36, s36, 0x100
	s_addc_u32 s37, s37, 0
	s_add_u32 s70, s11, s24
	s_addc_u32 s71, s64, s25
	s_cmpk_eq_i32 s24, 0xf00
	s_cselect_b32 s39, s19, s37
	s_cselect_b32 s38, s65, s36
	s_cselect_b32 s37, s17, s71
	s_cselect_b32 s36, s66, s70
	v_lshl_add_u64 v[190:191], v[144:145], 0, s[24:25]
	s_add_i32 m0, s40, 0xc000
	ds_read_b128 v[166:169], v149
	ds_read_b128 v[170:173], v149 offset:1024
	ds_read_b128 v[174:177], v149 offset:2048
	ds_read_b128 v[178:181], v149 offset:3072
	ds_read_b128 v[182:185], v149 offset:4096
	ds_read_b128 v[186:189], v149 offset:5120
	ds_read_b128 v[194:197], v149 offset:6144
	ds_read_b128 v[198:201], v149 offset:7168
	global_load_lds_dwordx4 v[190:191], off
	v_lshl_add_u64 v[190:191], v[146:147], 0, s[24:25]
	s_add_i32 m0, s40, 0xe000
	s_nop 0
	global_load_lds_dwordx4 v[190:191], off
	s_waitcnt lgkmcnt(8)
	s_barrier
	s_waitcnt lgkmcnt(0)
	s_setprio 1
	s_waitcnt lgkmcnt(0)
	v_mfma_f32_16x16x32_bf16 v[124:127], v[150:153], v[166:169], v[124:127]
	v_mfma_f32_16x16x32_bf16 v[120:123], v[158:161], v[166:169], v[120:123]
	v_mfma_f32_16x16x32_bf16 v[116:119], v[150:153], v[174:177], v[116:119]
	v_mfma_f32_16x16x32_bf16 v[112:115], v[158:161], v[174:177], v[112:115]
	v_mfma_f32_16x16x32_bf16 v[108:111], v[150:153], v[182:185], v[108:111]
	v_mfma_f32_16x16x32_bf16 v[104:107], v[158:161], v[182:185], v[104:107]
	v_mfma_f32_16x16x32_bf16 v[100:103], v[150:153], v[194:197], v[100:103]
	v_mfma_f32_16x16x32_bf16 v[96:99], v[158:161], v[194:197], v[96:99]
	v_mfma_f32_16x16x32_bf16 v[124:127], v[154:157], v[170:173], v[124:127]
	v_mfma_f32_16x16x32_bf16 v[120:123], v[162:165], v[170:173], v[120:123]
	v_mfma_f32_16x16x32_bf16 v[116:119], v[154:157], v[178:181], v[116:119]
	v_mfma_f32_16x16x32_bf16 v[112:115], v[162:165], v[178:181], v[112:115]
	v_mfma_f32_16x16x32_bf16 v[108:111], v[154:157], v[186:189], v[108:111]
	v_mfma_f32_16x16x32_bf16 v[104:107], v[162:165], v[186:189], v[104:107]
	v_mfma_f32_16x16x32_bf16 v[100:103], v[154:157], v[198:201], v[100:103]
	v_mfma_f32_16x16x32_bf16 v[96:99], v[162:165], v[198:201], v[96:99]
	s_setprio 0
	s_barrier
	v_add_u32_e32 v190, s55, v148
	s_add_i32 s70, s54, s34
	ds_read_b128 v[202:205], v190
	ds_read_b128 v[206:209], v190 offset:1024
	ds_read_b128 v[210:213], v190 offset:2048
	ds_read_b128 v[214:217], v190 offset:3072
	v_lshl_add_u64 v[190:191], s[36:37], 0, v[130:131]
	s_mov_b32 m0, s70
	v_lshl_add_u64 v[218:219], s[36:37], 0, v[128:129]
	global_load_lds_dwordx4 v[190:191], off
	s_add_i32 m0, s70, 0x2000
	s_nop 0
	global_load_lds_dwordx4 v[218:219], off
	s_barrier
	s_waitcnt lgkmcnt(0)
	s_setprio 1
	s_waitcnt lgkmcnt(0)
	v_mfma_f32_16x16x32_bf16 v[92:95], v[202:205], v[166:169], v[92:95]
	v_mfma_f32_16x16x32_bf16 v[88:91], v[210:213], v[166:169], v[88:91]
	v_mfma_f32_16x16x32_bf16 v[84:87], v[202:205], v[174:177], v[84:87]
	v_mfma_f32_16x16x32_bf16 v[80:83], v[210:213], v[174:177], v[80:83]
	v_mfma_f32_16x16x32_bf16 v[76:79], v[202:205], v[182:185], v[76:79]
	v_mfma_f32_16x16x32_bf16 v[72:75], v[210:213], v[182:185], v[72:75]
	v_mfma_f32_16x16x32_bf16 v[68:71], v[202:205], v[194:197], v[68:71]
	v_mfma_f32_16x16x32_bf16 v[64:67], v[210:213], v[194:197], v[64:67]
	v_mfma_f32_16x16x32_bf16 v[92:95], v[206:209], v[170:173], v[92:95]
	v_mfma_f32_16x16x32_bf16 v[88:91], v[214:217], v[170:173], v[88:91]
	v_mfma_f32_16x16x32_bf16 v[84:87], v[206:209], v[178:181], v[84:87]
	v_mfma_f32_16x16x32_bf16 v[80:83], v[214:217], v[178:181], v[80:83]
	v_mfma_f32_16x16x32_bf16 v[76:79], v[206:209], v[186:189], v[76:79]
	v_mfma_f32_16x16x32_bf16 v[72:75], v[214:217], v[186:189], v[72:75]
	v_mfma_f32_16x16x32_bf16 v[68:71], v[206:209], v[198:201], v[68:71]
	v_mfma_f32_16x16x32_bf16 v[64:67], v[214:217], v[198:201], v[64:67]
	s_setprio 0
	s_mov_b32 m0, s40
	v_lshl_add_u64 v[220:221], s[38:39], 0, v[130:131]
	s_barrier
	ds_read_b128 v[166:169], v149 offset:16384
	ds_read_b128 v[170:173], v149 offset:17408
	ds_read_b128 v[174:177], v149 offset:18432
	ds_read_b128 v[178:181], v149 offset:19456
	ds_read_b128 v[182:185], v149 offset:20480
	ds_read_b128 v[186:189], v149 offset:21504
	ds_read_b128 v[194:197], v149 offset:22528
	ds_read_b128 v[198:201], v149 offset:23552
	global_load_lds_dwordx4 v[220:221], off
	v_lshl_add_u64 v[222:223], s[38:39], 0, v[128:129]
	s_mov_b32 m0, s41
	s_nop 0
	global_load_lds_dwordx4 v[222:223], off
	s_barrier
	s_waitcnt lgkmcnt(0)
	s_setprio 1
	s_waitcnt lgkmcnt(0)
	v_mfma_f32_16x16x32_bf16 v[60:63], v[150:153], v[166:169], v[60:63]
	v_mfma_f32_16x16x32_bf16 v[56:59], v[158:161], v[166:169], v[56:59]
	v_mfma_f32_16x16x32_bf16 v[52:55], v[150:153], v[174:177], v[52:55]
	v_mfma_f32_16x16x32_bf16 v[48:51], v[158:161], v[174:177], v[48:51]
	v_mfma_f32_16x16x32_bf16 v[44:47], v[150:153], v[182:185], v[44:47]
	v_mfma_f32_16x16x32_bf16 v[40:43], v[158:161], v[182:185], v[40:43]
	v_mfma_f32_16x16x32_bf16 v[36:39], v[150:153], v[194:197], v[36:39]
	v_mfma_f32_16x16x32_bf16 v[32:35], v[158:161], v[194:197], v[32:35]
	v_mfma_f32_16x16x32_bf16 v[60:63], v[154:157], v[170:173], v[60:63]
	v_mfma_f32_16x16x32_bf16 v[56:59], v[162:165], v[170:173], v[56:59]
	v_mfma_f32_16x16x32_bf16 v[52:55], v[154:157], v[178:181], v[52:55]
	v_mfma_f32_16x16x32_bf16 v[48:51], v[162:165], v[178:181], v[48:51]
	v_mfma_f32_16x16x32_bf16 v[44:47], v[154:157], v[186:189], v[44:47]
	v_mfma_f32_16x16x32_bf16 v[40:43], v[162:165], v[186:189], v[40:43]
	v_mfma_f32_16x16x32_bf16 v[36:39], v[154:157], v[198:201], v[36:39]
	v_mfma_f32_16x16x32_bf16 v[32:35], v[162:165], v[198:201], v[32:35]
	s_setprio 0
	s_barrier
; #define PG8_STAGE(bufoff, gbase, voff) do { _Pragma("unroll") for (int _i = 0; _i < 2; ++_i) \
;         __builtin_amdgcn_global_load_lds((const unsigned*)((const char*)(gbase) + (voff)[_i]), (LAS unsigned*)(lds + (bufoff) + ldsw + _i * 8192), 16, 0, 0); } while (0)
; #define PG8_LDA(dst, b, h) do { _Pragma("unroll") for (int m = 0; m < 4; ++m) _Pragma("unroll") for (int k = 0; k < 2; ++k) dst[m][k] = *(const LAS bf16x8*)(lds + PG8_SA(b, h) + aoff + m * 2048 + k * 1024); } while (0)
; #define PG8_LDB(dst, b, h) do { _Pragma("unroll") for (int n = 0; n < 2; ++n) _Pragma("unroll") for (int k = 0; k < 2; ++k) dst[n][k] = *(const LAS bf16x8*)(lds + PG8_SB(b, h) + boff + n * 2048 + k * 1024); } while (0)
; #define PG8_MMA(ai, bj, At, Bt) do { __builtin_amdgcn_s_setprio(1); _Pragma("unroll") for (int m = 0; m < 4; ++m) _Pragma("unroll") for (int n = 0; n < 2; ++n) _Pragma("unroll") for (int k = 0; k < 2; ++k) \
;         acc[ai][bj][m][n] = __builtin_amdgcn_mfma_f32_16x16x32_bf16(Bt[n][k], At[m][k], acc[ai][bj][m][n], 0, 0, 0); __builtin_amdgcn_s_setprio(0); } while (0)
; #define PG8_WAIT_V(n) asm volatile("s_waitcnt vmcnt(" #n ")" ::: "memory")
; #define PG8_WAIT_L(n) asm volatile("s_waitcnt lgkmcnt(" #n ")" ::: "memory")
; #define PG8_BAR __builtin_amdgcn_s_barrier()
; #define PG8_SCHED __builtin_amdgcn_sched_barrier(0)
; template <class Epi>
; __device__ __forceinline__ void gemm_phase(LAS unsigned char* lds, const Gemm g, const Sched& S, const Epi& E) {
;     ...
;             PG8_STAGE(PG8_SB(0, 1), b2 + hstepB, voffB);
;             PG8_WAIT_V(6); PG8_BAR; PG8_MMA(1, 1, At, B1); PG8_BAR;
;             PG8_LDB(B0, 1, 0); PG8_SCHED; PG8_LDA(At, 1, 0); PG8_STAGE(PG8_SA(0, 1), a2 + hstepA, voffA);
;             PG8_WAIT_L(8); PG8_BAR; PG8_WAIT_L(0); PG8_MMA(0, 0, At, B0); PG8_BAR; PG8_SCHED;
;             PG8_LDB(B1, 1, 1); PG8_STAGE(PG8_SB(1, 0), b3, voffB);
;             PG8_BAR; PG8_WAIT_L(0); PG8_MMA(0, 1, At, B1); PG8_BAR;
;             PG8_LDA(At, 1, 1); PG8_STAGE(PG8_SA(1, 0), a3, voffA);
;             PG8_BAR; PG8_WAIT_L(0); PG8_MMA(1, 0, At, B0); PG8_BAR; PG8_SCHED;
	s_add_u32 s70, s36, 0x80000
	s_addc_u32 s71, s37, 0
	s_add_i32 s72, s55, s34
	v_lshl_add_u64 v[150:151], s[70:71], 0, v[130:131]
	s_mov_b32 m0, s72
	s_nop 0
	global_load_lds_dwordx4 v[150:151], off
	v_lshl_add_u64 v[150:151], s[70:71], 0, v[128:129]
	s_add_i32 m0, s72, 0x2000
	s_nop 0
	global_load_lds_dwordx4 v[150:151], off
	s_waitcnt vmcnt(6)
	s_barrier
	s_setprio 1
	v_mfma_f32_16x16x32_bf16 v[28:31], v[202:205], v[166:169], v[28:31]
	v_mfma_f32_16x16x32_bf16 v[24:27], v[210:213], v[166:169], v[24:27]
	v_mfma_f32_16x16x32_bf16 v[20:23], v[202:205], v[174:177], v[20:23]
	v_mfma_f32_16x16x32_bf16 v[16:19], v[210:213], v[174:177], v[16:19]
	v_mfma_f32_16x16x32_bf16 v[12:15], v[202:205], v[182:185], v[12:15]
	v_mfma_f32_16x16x32_bf16 v[8:11], v[210:213], v[182:185], v[8:11]
	v_mfma_f32_16x16x32_bf16 v[4:7], v[202:205], v[194:197], v[4:7]
	v_mfma_f32_16x16x32_bf16 v[0:3], v[210:213], v[194:197], v[0:3]
	v_mfma_f32_16x16x32_bf16 v[28:31], v[206:209], v[170:173], v[28:31]
	v_mfma_f32_16x16x32_bf16 v[24:27], v[214:217], v[170:173], v[24:27]
	v_mfma_f32_16x16x32_bf16 v[20:23], v[206:209], v[178:181], v[20:23]
	v_mfma_f32_16x16x32_bf16 v[16:19], v[214:217], v[178:181], v[16:19]
	v_mfma_f32_16x16x32_bf16 v[12:15], v[206:209], v[186:189], v[12:15]
	v_mfma_f32_16x16x32_bf16 v[8:11], v[214:217], v[186:189], v[8:11]
	v_mfma_f32_16x16x32_bf16 v[4:7], v[206:209], v[198:201], v[4:7]
	v_mfma_f32_16x16x32_bf16 v[0:3], v[214:217], v[198:201], v[0:3]
	s_setprio 0
	s_add_i32 s70, 0, 0x18000
	v_add_u32_e32 v162, s70, v148
	s_barrier
	ds_read_b128 v[150:153], v162
	ds_read_b128 v[154:157], v162 offset:1024
	ds_read_b128 v[158:161], v162 offset:2048
	ds_read_b128 v[162:165], v162 offset:3072
	s_add_u32 s38, s38, 0x80000
	s_addc_u32 s39, s39, 0
	s_mov_b32 m0, s43
	v_lshl_add_u64 v[202:203], s[38:39], 0, v[130:131]
	ds_read_b128 v[166:169], v149 offset:32768
	ds_read_b128 v[170:173], v149 offset:33792
	ds_read_b128 v[174:177], v149 offset:34816
	ds_read_b128 v[178:181], v149 offset:35840
	ds_read_b128 v[182:185], v149 offset:36864
	ds_read_b128 v[186:189], v149 offset:37888
	ds_read_b128 v[194:197], v149 offset:38912
	ds_read_b128 v[198:201], v149 offset:39936
	global_load_lds_dwordx4 v[202:203], off
	v_lshl_add_u64 v[202:203], s[38:39], 0, v[128:129]
	s_mov_b32 m0, s46
	s_nop 0
	global_load_lds_dwordx4 v[202:203], off
	s_waitcnt lgkmcnt(8)
	s_barrier
	s_waitcnt lgkmcnt(0)
	s_setprio 1
	s_waitcnt lgkmcnt(0)
	v_mfma_f32_16x16x32_bf16 v[124:127], v[150:153], v[166:169], v[124:127]
	v_mfma_f32_16x16x32_bf16 v[120:123], v[158:161], v[166:169], v[120:123]
	v_mfma_f32_16x16x32_bf16 v[116:119], v[150:153], v[174:177], v[116:119]
	v_mfma_f32_16x16x32_bf16 v[112:115], v[158:161], v[174:177], v[112:115]
	v_mfma_f32_16x16x32_bf16 v[108:111], v[150:153], v[182:185], v[108:111]
	v_mfma_f32_16x16x32_bf16 v[104:107], v[158:161], v[182:185], v[104:107]
	v_mfma_f32_16x16x32_bf16 v[100:103], v[150:153], v[194:197], v[100:103]
	v_mfma_f32_16x16x32_bf16 v[96:99], v[158:161], v[194:197], v[96:99]
	v_mfma_f32_16x16x32_bf16 v[124:127], v[154:157], v[170:173], v[124:127]
	v_mfma_f32_16x16x32_bf16 v[120:123], v[162:165], v[170:173], v[120:123]
	v_mfma_f32_16x16x32_bf16 v[116:119], v[154:157], v[178:181], v[116:119]
	v_mfma_f32_16x16x32_bf16 v[112:115], v[162:165], v[178:181], v[112:115]
	v_mfma_f32_16x16x32_bf16 v[108:111], v[154:157], v[186:189], v[108:111]
	v_mfma_f32_16x16x32_bf16 v[104:107], v[162:165], v[186:189], v[104:107]
	v_mfma_f32_16x16x32_bf16 v[100:103], v[154:157], v[198:201], v[100:103]
	v_mfma_f32_16x16x32_bf16 v[96:99], v[162:165], v[198:201], v[96:99]
	s_setprio 0
	s_barrier
	s_add_i32 s38, 0, 0x1c000
	s_add_i32 s39, s70, s34
	v_add_u32_e32 v214, s38, v148
	v_lshl_add_u64 v[190:191], v[190:191], 0, s[14:15]
	s_mov_b32 m0, s39
	ds_read_b128 v[202:205], v214
	ds_read_b128 v[206:209], v214 offset:1024
	ds_read_b128 v[210:213], v214 offset:2048
	ds_read_b128 v[214:217], v214 offset:3072
	global_load_lds_dwordx4 v[190:191], off
	v_lshl_add_u64 v[190:191], v[218:219], 0, s[14:15]
	s_add_i32 m0, s39, 0x2000
	s_nop 0
	global_load_lds_dwordx4 v[190:191], off
	s_barrier
	s_waitcnt lgkmcnt(0)
	s_setprio 1
	s_waitcnt lgkmcnt(0)
	v_mfma_f32_16x16x32_bf16 v[92:95], v[202:205], v[166:169], v[92:95]
	v_mfma_f32_16x16x32_bf16 v[88:91], v[210:213], v[166:169], v[88:91]
	v_mfma_f32_16x16x32_bf16 v[84:87], v[202:205], v[174:177], v[84:87]
	v_mfma_f32_16x16x32_bf16 v[80:83], v[210:213], v[174:177], v[80:83]
	v_mfma_f32_16x16x32_bf16 v[76:79], v[202:205], v[182:185], v[76:79]
	v_mfma_f32_16x16x32_bf16 v[72:75], v[210:213], v[182:185], v[72:75]
	v_mfma_f32_16x16x32_bf16 v[68:71], v[202:205], v[194:197], v[68:71]
	v_mfma_f32_16x16x32_bf16 v[64:67], v[210:213], v[194:197], v[64:67]
	v_mfma_f32_16x16x32_bf16 v[92:95], v[206:209], v[170:173], v[92:95]
	v_mfma_f32_16x16x32_bf16 v[88:91], v[214:217], v[170:173], v[88:91]
	v_mfma_f32_16x16x32_bf16 v[84:87], v[206:209], v[178:181], v[84:87]
	v_mfma_f32_16x16x32_bf16 v[80:83], v[214:217], v[178:181], v[80:83]
	v_mfma_f32_16x16x32_bf16 v[76:79], v[206:209], v[186:189], v[76:79]
	v_mfma_f32_16x16x32_bf16 v[72:75], v[214:217], v[186:189], v[72:75]
	v_mfma_f32_16x16x32_bf16 v[68:71], v[206:209], v[198:201], v[68:71]
	v_mfma_f32_16x16x32_bf16 v[64:67], v[214:217], v[198:201], v[64:67]
	s_setprio 0
	s_mov_b32 m0, s52
	v_lshl_add_u64 v[190:191], v[220:221], 0, s[14:15]
	s_barrier
	ds_read_b128 v[166:169], v149 offset:49152
	ds_read_b128 v[170:173], v149 offset:50176
	ds_read_b128 v[174:177], v149 offset:51200
	ds_read_b128 v[178:181], v149 offset:52224
	ds_read_b128 v[182:185], v149 offset:53248
	ds_read_b128 v[186:189], v149 offset:54272
	ds_read_b128 v[194:197], v149 offset:55296
	ds_read_b128 v[198:201], v149 offset:56320
	global_load_lds_dwordx4 v[190:191], off
	v_lshl_add_u64 v[190:191], v[222:223], 0, s[14:15]
	s_mov_b32 m0, s53
	s_nop 0
	global_load_lds_dwordx4 v[190:191], off
	s_barrier
; __device__ __forceinline__ unsigned cvt_pk_bf16(float lo, float hi) { unsigned r; asm volatile("v_cvt_pk_bf16_f32 %0, %1, %2" : "=v"(r) : "v"(lo), "v"(hi)); return r; }
; #define PG8_STAGE(bufoff, gbase, voff) do { _Pragma("unroll") for (int _i = 0; _i < 2; ++_i) \
;         __builtin_amdgcn_global_load_lds((const unsigned*)((const char*)(gbase) + (voff)[_i]), (LAS unsigned*)(lds + (bufoff) + ldsw + _i * 8192), 16, 0, 0); } while (0)
; #define PG8_LDA(dst, b, h) do { _Pragma("unroll") for (int m = 0; m < 4; ++m) _Pragma("unroll") for (int k = 0; k < 2; ++k) dst[m][k] = *(const LAS bf16x8*)(lds + PG8_SA(b, h) + aoff + m * 2048 + k * 1024); } while (0)
; #define PG8_MMA(ai, bj, At, Bt) do { __builtin_amdgcn_s_setprio(1); _Pragma("unroll") for (int m = 0; m < 4; ++m) _Pragma("unroll") for (int n = 0; n < 2; ++n) _Pragma("unroll") for (int k = 0; k < 2; ++k) \
;         acc[ai][bj][m][n] = __builtin_amdgcn_mfma_f32_16x16x32_bf16(Bt[n][k], At[m][k], acc[ai][bj][m][n], 0, 0, 0); __builtin_amdgcn_s_setprio(0); } while (0)
; template <class Epi>
; __device__ __forceinline__ void gemm_phase(LAS unsigned char* lds, const Gemm g, const Sched& S, const Epi& E) {
;     ...
;             PG8_BAR; PG8_WAIT_L(0); PG8_MMA(0, 1, At, B1); PG8_BAR;
;             PG8_LDA(At, 1, 1); PG8_STAGE(PG8_SA(1, 0), a3, voffA);
;             PG8_BAR; PG8_WAIT_L(0); PG8_MMA(1, 0, At, B0); PG8_BAR; PG8_SCHED;
;             PG8_STAGE(PG8_SB(1, 1), b3 + hstepB, voffB);
;             PG8_WAIT_V(6); PG8_BAR; PG8_MMA(1, 1, At, B1); PG8_BAR;
;         }
;         E(acc, cur, wr, wc, fr, fq);
;     __device__ __forceinline__ void operator()(AccRef acc, const Unit& u, int wr, int wc, int fr, int fq) const {
;     ...
;         for (int ai = 0; ai < 2; ++ai)
; #pragma unroll
;             for (int m = 0; m < 4; ++m) { const size_t row = (size_t)u.pm * 256 + ai * 128 + wr * 64 + m * 16 + fr; float o[8];
; #pragma unroll
;                 for (int bj = 0; bj < 2; ++bj) { const f32x4 gg = acc[ai][bj][m][0], uu = acc[ai][bj][m][1];
; #pragma unroll
;                     for (int j = 0; j < 4; ++j) o[4 * bj + j] = gg[j] * __builtin_amdgcn_rcpf(1.0f + __expf(-gg[j])) * uu[j]; }
;                 u32x4 w; w.x = cvt_pk_bf16(o[0], o[1]); w.y = cvt_pk_bf16(o[2], o[3]); w.z = cvt_pk_bf16(o[4], o[5]); w.w = cvt_pk_bf16(o[6], o[7]);
;                 *(u32x4*)(act + row * FF_ + (u.pn * 4 + wc) * 32 + 8 * fq) = w; }
	s_waitcnt lgkmcnt(0)
	s_setprio 1
	s_waitcnt lgkmcnt(0)
	v_mfma_f32_16x16x32_bf16 v[60:63], v[150:153], v[166:169], v[60:63]
	v_mfma_f32_16x16x32_bf16 v[56:59], v[158:161], v[166:169], v[56:59]
	v_mfma_f32_16x16x32_bf16 v[52:55], v[150:153], v[174:177], v[52:55]
	v_mfma_f32_16x16x32_bf16 v[48:51], v[158:161], v[174:177], v[48:51]
	v_mfma_f32_16x16x32_bf16 v[44:47], v[150:153], v[182:185], v[44:47]
	v_mfma_f32_16x16x32_bf16 v[40:43], v[158:161], v[182:185], v[40:43]
	v_mfma_f32_16x16x32_bf16 v[36:39], v[150:153], v[194:197], v[36:39]
	v_mfma_f32_16x16x32_bf16 v[32:35], v[158:161], v[194:197], v[32:35]
	v_mfma_f32_16x16x32_bf16 v[60:63], v[154:157], v[170:173], v[60:63]
	v_mfma_f32_16x16x32_bf16 v[56:59], v[162:165], v[170:173], v[56:59]
	v_mfma_f32_16x16x32_bf16 v[52:55], v[154:157], v[178:181], v[52:55]
	v_mfma_f32_16x16x32_bf16 v[48:51], v[162:165], v[178:181], v[48:51]
	v_mfma_f32_16x16x32_bf16 v[44:47], v[154:157], v[186:189], v[44:47]
	v_mfma_f32_16x16x32_bf16 v[40:43], v[162:165], v[186:189], v[40:43]
	v_mfma_f32_16x16x32_bf16 v[36:39], v[154:157], v[198:201], v[36:39]
	v_mfma_f32_16x16x32_bf16 v[32:35], v[162:165], v[198:201], v[32:35]
	s_setprio 0
	s_barrier
	s_add_u32 s36, s36, 0x80080
	s_addc_u32 s37, s37, 0
	s_add_i32 s38, s38, s34
	v_lshl_add_u64 v[150:151], s[36:37], 0, v[130:131]
	s_mov_b32 m0, s38
	s_nop 0
	global_load_lds_dwordx4 v[150:151], off
	v_lshl_add_u64 v[150:151], s[36:37], 0, v[128:129]
	s_add_i32 m0, s38, 0x2000
	s_nop 0
	global_load_lds_dwordx4 v[150:151], off
	s_waitcnt vmcnt(6)
	s_barrier
	s_setprio 1
	v_mfma_f32_16x16x32_bf16 v[28:31], v[202:205], v[166:169], v[28:31]
	v_mfma_f32_16x16x32_bf16 v[24:27], v[210:213], v[166:169], v[24:27]
	v_mfma_f32_16x16x32_bf16 v[20:23], v[202:205], v[174:177], v[20:23]
	v_mfma_f32_16x16x32_bf16 v[16:19], v[210:213], v[174:177], v[16:19]
	v_mfma_f32_16x16x32_bf16 v[12:15], v[202:205], v[182:185], v[12:15]
	v_mfma_f32_16x16x32_bf16 v[8:11], v[210:213], v[182:185], v[8:11]
	v_mfma_f32_16x16x32_bf16 v[4:7], v[202:205], v[194:197], v[4:7]
	v_mfma_f32_16x16x32_bf16 v[0:3], v[210:213], v[194:197], v[0:3]
	v_mfma_f32_16x16x32_bf16 v[28:31], v[206:209], v[170:173], v[28:31]
	v_mfma_f32_16x16x32_bf16 v[24:27], v[214:217], v[170:173], v[24:27]
	v_mfma_f32_16x16x32_bf16 v[20:23], v[206:209], v[178:181], v[20:23]
	v_mfma_f32_16x16x32_bf16 v[16:19], v[214:217], v[178:181], v[16:19]
	v_mfma_f32_16x16x32_bf16 v[12:15], v[206:209], v[186:189], v[12:15]
	v_mfma_f32_16x16x32_bf16 v[8:11], v[214:217], v[186:189], v[8:11]
	v_mfma_f32_16x16x32_bf16 v[4:7], v[206:209], v[198:201], v[4:7]
	v_mfma_f32_16x16x32_bf16 v[0:3], v[214:217], v[198:201], v[0:3]
	s_setprio 0
	s_add_i32 s67, s67, 2
	s_add_u32 s24, s24, 0x100
	s_addc_u32 s25, s25, 0
	s_cmp_gt_u32 s67, 29
	s_barrier
	s_cbranch_scc0 .LBB0_3085
	v_mov_b32_e32 v170, 0xbfb8aa3b
	v_mov_b32_e32 v172, 1.0
	s_add_u32 s24, s11, 0xffffff00
	s_addc_u32 s25, s64, -1
	s_ashr_i32 s11, s10, 31
	s_lshl_b64 s[36:37], s[10:11], 8
	v_lshl_add_u64 v[144:145], v[134:135], 0, s[36:37]
	v_mov_b64_e32 v[146:147], s[44:45]
	v_mad_u64_u32 v[146:147], s[38:39], v144, s56, v[146:147]
	s_lshl_b32 s11, s50, 7
	v_mov_b32_e32 v144, v147
	s_or_b32 s36, s11, s51
	v_mad_u64_u32 v[144:145], s[38:39], v145, s56, v[144:145]
	s_ashr_i32 s37, s36, 31
	v_mov_b32_e32 v147, v144
	v_lshl_add_u64 v[144:145], s[36:37], 1, v[146:147]
	v_lshl_add_u64 v[144:145], v[144:145], 0, v[132:133]
	v_pk_mul_f32 v[162:163], v[124:125], v[170:171] op_sel_hi:[1,0]
	v_pk_mul_f32 v[164:165], v[126:127], v[170:171] op_sel_hi:[1,0]
	v_pk_mul_f32 v[166:167], v[92:93], v[170:171] op_sel_hi:[1,0]
	v_pk_mul_f32 v[168:169], v[94:95], v[170:171] op_sel_hi:[1,0]
	v_exp_f32_e32 v162, v162
	v_exp_f32_e32 v163, v163
	v_exp_f32_e32 v164, v164
	v_exp_f32_e32 v165, v165
	v_exp_f32_e32 v166, v166
	v_exp_f32_e32 v167, v167
	v_exp_f32_e32 v168, v168
	v_exp_f32_e32 v169, v169
	v_pk_add_f32 v[162:163], v[162:163], v[172:173] op_sel_hi:[1,0]
	v_pk_add_f32 v[164:165], v[164:165], v[172:173] op_sel_hi:[1,0]
	v_pk_add_f32 v[166:167], v[166:167], v[172:173] op_sel_hi:[1,0]
	v_pk_add_f32 v[168:169], v[168:169], v[172:173] op_sel_hi:[1,0]
	v_rcp_f32_e32 v162, v162
	v_rcp_f32_e32 v163, v163
	v_rcp_f32_e32 v164, v164
	v_rcp_f32_e32 v165, v165
	v_rcp_f32_e32 v166, v166
	v_rcp_f32_e32 v167, v167
	v_rcp_f32_e32 v168, v168
	v_rcp_f32_e32 v169, v169
	v_pk_mul_f32 v[162:163], v[124:125], v[162:163]
	v_pk_mul_f32 v[164:165], v[126:127], v[164:165]
	v_pk_mul_f32 v[166:167], v[92:93], v[166:167]
	v_pk_mul_f32 v[168:169], v[94:95], v[168:169]
	v_pk_mul_f32 v[162:163], v[120:121], v[162:163]
	v_pk_mul_f32 v[164:165], v[122:123], v[164:165]
	v_pk_mul_f32 v[166:167], v[88:89], v[166:167]
	v_pk_mul_f32 v[168:169], v[90:91], v[168:169]
	v_cvt_pk_bf16_f32 v150, v162, v163
	v_cvt_pk_bf16_f32 v151, v164, v165
	v_cvt_pk_bf16_f32 v152, v166, v167
	v_cvt_pk_bf16_f32 v153, v168, v169
	global_store_dwordx4 v[144:145], v[150:153], off
	v_add_co_u32_e32 v146, vcc, s57, v144
	s_nop 0
	v_addc_co_u32_e32 v147, vcc, 0, v145, vcc
	v_pk_mul_f32 v[162:163], v[116:117], v[170:171] op_sel_hi:[1,0]
	v_pk_mul_f32 v[164:165], v[118:119], v[170:171] op_sel_hi:[1,0]
	v_pk_mul_f32 v[166:167], v[84:85], v[170:171] op_sel_hi:[1,0]
	v_pk_mul_f32 v[168:169], v[86:87], v[170:171] op_sel_hi:[1,0]
	v_exp_f32_e32 v162, v162
	v_exp_f32_e32 v163, v163
	v_exp_f32_e32 v164, v164
	v_exp_f32_e32 v165, v165
	v_exp_f32_e32 v166, v166
	v_exp_f32_e32 v167, v167
	v_exp_f32_e32 v168, v168
	v_exp_f32_e32 v169, v169
	v_pk_add_f32 v[162:163], v[162:163], v[172:173] op_sel_hi:[1,0]
	v_pk_add_f32 v[164:165], v[164:165], v[172:173] op_sel_hi:[1,0]
	v_pk_add_f32 v[166:167], v[166:167], v[172:173] op_sel_hi:[1,0]
; __device__ __forceinline__ unsigned cvt_pk_bf16(float lo, float hi) { unsigned r; asm volatile("v_cvt_pk_bf16_f32 %0, %1, %2" : "=v"(r) : "v"(lo), "v"(hi)); return r; }
;     __device__ __forceinline__ void operator()(AccRef acc, const Unit& u, int wr, int wc, int fr, int fq) const {
;     ...
;         for (int ai = 0; ai < 2; ++ai)
; #pragma unroll
;             for (int m = 0; m < 4; ++m) { const size_t row = (size_t)u.pm * 256 + ai * 128 + wr * 64 + m * 16 + fr; float o[8];
; #pragma unroll
;                 for (int bj = 0; bj < 2; ++bj) { const f32x4 gg = acc[ai][bj][m][0], uu = acc[ai][bj][m][1];
; #pragma unroll
;                     for (int j = 0; j < 4; ++j) o[4 * bj + j] = gg[j] * __builtin_amdgcn_rcpf(1.0f + __expf(-gg[j])) * uu[j]; }
;                 u32x4 w; w.x = cvt_pk_bf16(o[0], o[1]); w.y = cvt_pk_bf16(o[2], o[3]); w.z = cvt_pk_bf16(o[4], o[5]); w.w = cvt_pk_bf16(o[6], o[7]);
;                 *(u32x4*)(act + row * FF_ + (u.pn * 4 + wc) * 32 + 8 * fq) = w; }
	v_pk_add_f32 v[168:169], v[168:169], v[172:173] op_sel_hi:[1,0]
	v_rcp_f32_e32 v162, v162
	v_rcp_f32_e32 v163, v163
	v_rcp_f32_e32 v164, v164
	v_rcp_f32_e32 v165, v165
	v_rcp_f32_e32 v166, v166
	v_rcp_f32_e32 v167, v167
	v_rcp_f32_e32 v168, v168
	v_rcp_f32_e32 v169, v169
	v_pk_mul_f32 v[162:163], v[116:117], v[162:163]
	v_pk_mul_f32 v[164:165], v[118:119], v[164:165]
	v_pk_mul_f32 v[166:167], v[84:85], v[166:167]
	v_pk_mul_f32 v[168:169], v[86:87], v[168:169]
	v_pk_mul_f32 v[162:163], v[112:113], v[162:163]
	v_pk_mul_f32 v[164:165], v[114:115], v[164:165]
	v_pk_mul_f32 v[166:167], v[80:81], v[166:167]
	v_pk_mul_f32 v[168:169], v[82:83], v[168:169]
	v_cvt_pk_bf16_f32 v150, v162, v163
	v_cvt_pk_bf16_f32 v151, v164, v165
	v_cvt_pk_bf16_f32 v152, v166, v167
	v_cvt_pk_bf16_f32 v153, v168, v169
	global_store_dwordx4 v[146:147], v[150:153], off
	v_add_co_u32_e32 v146, vcc, s58, v144
	s_nop 0
	v_addc_co_u32_e32 v147, vcc, 0, v145, vcc
	v_pk_mul_f32 v[162:163], v[108:109], v[170:171] op_sel_hi:[1,0]
	v_pk_mul_f32 v[164:165], v[110:111], v[170:171] op_sel_hi:[1,0]
	v_pk_mul_f32 v[166:167], v[76:77], v[170:171] op_sel_hi:[1,0]
	v_pk_mul_f32 v[168:169], v[78:79], v[170:171] op_sel_hi:[1,0]
	v_exp_f32_e32 v162, v162
	v_exp_f32_e32 v163, v163
	v_exp_f32_e32 v164, v164
	v_exp_f32_e32 v165, v165
	v_exp_f32_e32 v166, v166
	v_exp_f32_e32 v167, v167
	v_exp_f32_e32 v168, v168
	v_exp_f32_e32 v169, v169
	v_pk_add_f32 v[162:163], v[162:163], v[172:173] op_sel_hi:[1,0]
	v_pk_add_f32 v[164:165], v[164:165], v[172:173] op_sel_hi:[1,0]
	v_pk_add_f32 v[166:167], v[166:167], v[172:173] op_sel_hi:[1,0]
	v_pk_add_f32 v[168:169], v[168:169], v[172:173] op_sel_hi:[1,0]
	v_rcp_f32_e32 v162, v162
	v_rcp_f32_e32 v163, v163
	v_rcp_f32_e32 v164, v164
	v_rcp_f32_e32 v165, v165
	v_rcp_f32_e32 v166, v166
	v_rcp_f32_e32 v167, v167
	v_rcp_f32_e32 v168, v168
	v_rcp_f32_e32 v169, v169
	v_pk_mul_f32 v[162:163], v[108:109], v[162:163]
	v_pk_mul_f32 v[164:165], v[110:111], v[164:165]
	v_pk_mul_f32 v[166:167], v[76:77], v[166:167]
	v_pk_mul_f32 v[168:169], v[78:79], v[168:169]
	v_pk_mul_f32 v[162:163], v[104:105], v[162:163]
	v_pk_mul_f32 v[164:165], v[106:107], v[164:165]
	v_pk_mul_f32 v[166:167], v[72:73], v[166:167]
	v_pk_mul_f32 v[168:169], v[74:75], v[168:169]
	v_cvt_pk_bf16_f32 v150, v162, v163
	v_cvt_pk_bf16_f32 v151, v164, v165
	v_cvt_pk_bf16_f32 v152, v166, v167
	v_cvt_pk_bf16_f32 v153, v168, v169
	global_store_dwordx4 v[146:147], v[150:153], off
	v_add_co_u32_e32 v146, vcc, s59, v144
	s_nop 0
	v_addc_co_u32_e32 v147, vcc, 0, v145, vcc
	v_pk_mul_f32 v[162:163], v[100:101], v[170:171] op_sel_hi:[1,0]
	v_pk_mul_f32 v[164:165], v[102:103], v[170:171] op_sel_hi:[1,0]
	v_pk_mul_f32 v[166:167], v[68:69], v[170:171] op_sel_hi:[1,0]
	v_pk_mul_f32 v[168:169], v[70:71], v[170:171] op_sel_hi:[1,0]
	v_exp_f32_e32 v162, v162
	v_exp_f32_e32 v163, v163
	v_exp_f32_e32 v164, v164
	v_exp_f32_e32 v165, v165
	v_exp_f32_e32 v166, v166
	v_exp_f32_e32 v167, v167
	v_exp_f32_e32 v168, v168
	v_exp_f32_e32 v169, v169
	v_pk_add_f32 v[162:163], v[162:163], v[172:173] op_sel_hi:[1,0]
	v_pk_add_f32 v[164:165], v[164:165], v[172:173] op_sel_hi:[1,0]
	v_pk_add_f32 v[166:167], v[166:167], v[172:173] op_sel_hi:[1,0]
	v_pk_add_f32 v[168:169], v[168:169], v[172:173] op_sel_hi:[1,0]
	v_rcp_f32_e32 v162, v162
	v_rcp_f32_e32 v163, v163
	v_rcp_f32_e32 v164, v164
	v_rcp_f32_e32 v165, v165
	v_rcp_f32_e32 v166, v166
	v_rcp_f32_e32 v167, v167
	v_rcp_f32_e32 v168, v168
	v_rcp_f32_e32 v169, v169
	v_pk_mul_f32 v[162:163], v[100:101], v[162:163]
	v_pk_mul_f32 v[164:165], v[102:103], v[164:165]
	v_pk_mul_f32 v[166:167], v[68:69], v[166:167]
	v_pk_mul_f32 v[168:169], v[70:71], v[168:169]
	v_pk_mul_f32 v[162:163], v[96:97], v[162:163]
	v_pk_mul_f32 v[164:165], v[98:99], v[164:165]
	v_pk_mul_f32 v[166:167], v[64:65], v[166:167]
	v_pk_mul_f32 v[168:169], v[66:67], v[168:169]
	v_cvt_pk_bf16_f32 v150, v162, v163
	v_cvt_pk_bf16_f32 v151, v164, v165
	v_cvt_pk_bf16_f32 v152, v166, v167
	v_cvt_pk_bf16_f32 v153, v168, v169
	global_store_dwordx4 v[146:147], v[150:153], off
	v_add_co_u32_e32 v146, vcc, s60, v144
	s_nop 0
	v_addc_co_u32_e32 v147, vcc, 0, v145, vcc
	v_pk_mul_f32 v[162:163], v[60:61], v[170:171] op_sel_hi:[1,0]
	v_pk_mul_f32 v[164:165], v[62:63], v[170:171] op_sel_hi:[1,0]
	v_pk_mul_f32 v[166:167], v[28:29], v[170:171] op_sel_hi:[1,0]
	v_pk_mul_f32 v[168:169], v[30:31], v[170:171] op_sel_hi:[1,0]
	v_exp_f32_e32 v162, v162
	v_exp_f32_e32 v163, v163
	v_exp_f32_e32 v164, v164
	v_exp_f32_e32 v165, v165
	v_exp_f32_e32 v166, v166
	v_exp_f32_e32 v167, v167
	v_exp_f32_e32 v168, v168
	v_exp_f32_e32 v169, v169
	v_pk_add_f32 v[162:163], v[162:163], v[172:173] op_sel_hi:[1,0]
	v_pk_add_f32 v[164:165], v[164:165], v[172:173] op_sel_hi:[1,0]
	v_pk_add_f32 v[166:167], v[166:167], v[172:173] op_sel_hi:[1,0]
	v_pk_add_f32 v[168:169], v[168:169], v[172:173] op_sel_hi:[1,0]
	v_rcp_f32_e32 v162, v162
	v_rcp_f32_e32 v163, v163
	v_rcp_f32_e32 v164, v164
	v_rcp_f32_e32 v165, v165
	v_rcp_f32_e32 v166, v166
	v_rcp_f32_e32 v167, v167
	v_rcp_f32_e32 v168, v168
	v_rcp_f32_e32 v169, v169
	v_pk_mul_f32 v[162:163], v[60:61], v[162:163]
	v_pk_mul_f32 v[164:165], v[62:63], v[164:165]
	v_pk_mul_f32 v[166:167], v[28:29], v[166:167]
	v_pk_mul_f32 v[168:169], v[30:31], v[168:169]
	v_pk_mul_f32 v[162:163], v[56:57], v[162:163]
; __device__ __forceinline__ unsigned cvt_pk_bf16(float lo, float hi) { unsigned r; asm volatile("v_cvt_pk_bf16_f32 %0, %1, %2" : "=v"(r) : "v"(lo), "v"(hi)); return r; }
;     __device__ __forceinline__ void operator()(AccRef acc, const Unit& u, int wr, int wc, int fr, int fq) const {
;     ...
;         for (int ai = 0; ai < 2; ++ai)
; #pragma unroll
;             for (int m = 0; m < 4; ++m) { const size_t row = (size_t)u.pm * 256 + ai * 128 + wr * 64 + m * 16 + fr; float o[8];
; #pragma unroll
;                 for (int bj = 0; bj < 2; ++bj) { const f32x4 gg = acc[ai][bj][m][0], uu = acc[ai][bj][m][1];
; #pragma unroll
;                     for (int j = 0; j < 4; ++j) o[4 * bj + j] = gg[j] * __builtin_amdgcn_rcpf(1.0f + __expf(-gg[j])) * uu[j]; }
;                 u32x4 w; w.x = cvt_pk_bf16(o[0], o[1]); w.y = cvt_pk_bf16(o[2], o[3]); w.z = cvt_pk_bf16(o[4], o[5]); w.w = cvt_pk_bf16(o[6], o[7]);
;                 *(u32x4*)(act + row * FF_ + (u.pn * 4 + wc) * 32 + 8 * fq) = w; }
	v_pk_mul_f32 v[164:165], v[58:59], v[164:165]
	v_pk_mul_f32 v[166:167], v[24:25], v[166:167]
	v_pk_mul_f32 v[168:169], v[26:27], v[168:169]
	v_cvt_pk_bf16_f32 v150, v162, v163
	v_cvt_pk_bf16_f32 v151, v164, v165
	v_cvt_pk_bf16_f32 v152, v166, v167
	v_cvt_pk_bf16_f32 v153, v168, v169
	global_store_dwordx4 v[146:147], v[150:153], off
	v_add_co_u32_e32 v146, vcc, s61, v144
	s_nop 0
	v_addc_co_u32_e32 v147, vcc, 0, v145, vcc
	v_pk_mul_f32 v[162:163], v[52:53], v[170:171] op_sel_hi:[1,0]
	v_pk_mul_f32 v[164:165], v[54:55], v[170:171] op_sel_hi:[1,0]
	v_pk_mul_f32 v[166:167], v[20:21], v[170:171] op_sel_hi:[1,0]
	v_pk_mul_f32 v[168:169], v[22:23], v[170:171] op_sel_hi:[1,0]
	v_exp_f32_e32 v162, v162
	v_exp_f32_e32 v163, v163
	v_exp_f32_e32 v164, v164
	v_exp_f32_e32 v165, v165
	v_exp_f32_e32 v166, v166
	v_exp_f32_e32 v167, v167
	v_exp_f32_e32 v168, v168
	v_exp_f32_e32 v169, v169
	v_pk_add_f32 v[162:163], v[162:163], v[172:173] op_sel_hi:[1,0]
	v_pk_add_f32 v[164:165], v[164:165], v[172:173] op_sel_hi:[1,0]
	v_pk_add_f32 v[166:167], v[166:167], v[172:173] op_sel_hi:[1,0]
	v_pk_add_f32 v[168:169], v[168:169], v[172:173] op_sel_hi:[1,0]
	v_rcp_f32_e32 v162, v162
	v_rcp_f32_e32 v163, v163
	v_rcp_f32_e32 v164, v164
	v_rcp_f32_e32 v165, v165
	v_rcp_f32_e32 v166, v166
	v_rcp_f32_e32 v167, v167
	v_rcp_f32_e32 v168, v168
	v_rcp_f32_e32 v169, v169
	v_pk_mul_f32 v[162:163], v[52:53], v[162:163]
	v_pk_mul_f32 v[164:165], v[54:55], v[164:165]
	v_pk_mul_f32 v[166:167], v[20:21], v[166:167]
	v_pk_mul_f32 v[168:169], v[22:23], v[168:169]
	v_pk_mul_f32 v[162:163], v[48:49], v[162:163]
	v_pk_mul_f32 v[164:165], v[50:51], v[164:165]
	v_pk_mul_f32 v[166:167], v[16:17], v[166:167]
	v_pk_mul_f32 v[168:169], v[18:19], v[168:169]
	v_cvt_pk_bf16_f32 v150, v162, v163
	v_cvt_pk_bf16_f32 v151, v164, v165
	v_cvt_pk_bf16_f32 v152, v166, v167
	v_cvt_pk_bf16_f32 v153, v168, v169
	global_store_dwordx4 v[146:147], v[150:153], off
	v_add_co_u32_e32 v146, vcc, s62, v144
	s_nop 0
	v_addc_co_u32_e32 v147, vcc, 0, v145, vcc
	v_pk_mul_f32 v[162:163], v[44:45], v[170:171] op_sel_hi:[1,0]
	v_pk_mul_f32 v[164:165], v[46:47], v[170:171] op_sel_hi:[1,0]
	v_pk_mul_f32 v[166:167], v[12:13], v[170:171] op_sel_hi:[1,0]
	v_pk_mul_f32 v[168:169], v[14:15], v[170:171] op_sel_hi:[1,0]
	v_exp_f32_e32 v162, v162
	v_exp_f32_e32 v163, v163
	v_exp_f32_e32 v164, v164
	v_exp_f32_e32 v165, v165
	v_exp_f32_e32 v166, v166
	v_exp_f32_e32 v167, v167
	v_exp_f32_e32 v168, v168
	v_exp_f32_e32 v169, v169
	v_pk_add_f32 v[162:163], v[162:163], v[172:173] op_sel_hi:[1,0]
	v_pk_add_f32 v[164:165], v[164:165], v[172:173] op_sel_hi:[1,0]
	v_pk_add_f32 v[166:167], v[166:167], v[172:173] op_sel_hi:[1,0]
	v_pk_add_f32 v[168:169], v[168:169], v[172:173] op_sel_hi:[1,0]
	v_rcp_f32_e32 v162, v162
	v_rcp_f32_e32 v163, v163
	v_rcp_f32_e32 v164, v164
	v_rcp_f32_e32 v165, v165
	v_rcp_f32_e32 v166, v166
	v_rcp_f32_e32 v167, v167
	v_rcp_f32_e32 v168, v168
	v_rcp_f32_e32 v169, v169
	v_pk_mul_f32 v[162:163], v[44:45], v[162:163]
	v_pk_mul_f32 v[164:165], v[46:47], v[164:165]
	v_pk_mul_f32 v[166:167], v[12:13], v[166:167]
	v_pk_mul_f32 v[168:169], v[14:15], v[168:169]
	v_pk_mul_f32 v[162:163], v[40:41], v[162:163]
	v_pk_mul_f32 v[164:165], v[42:43], v[164:165]
	v_pk_mul_f32 v[166:167], v[8:9], v[166:167]
	v_pk_mul_f32 v[168:169], v[10:11], v[168:169]
	v_cvt_pk_bf16_f32 v150, v162, v163
	v_cvt_pk_bf16_f32 v151, v164, v165
	v_cvt_pk_bf16_f32 v152, v166, v167
	v_cvt_pk_bf16_f32 v153, v168, v169
	global_store_dwordx4 v[146:147], v[150:153], off
	v_add_co_u32_e32 v144, vcc, 0x1e4000, v144
	v_addc_co_u32_e32 v145, vcc, 0, v145, vcc
	s_andn2_b64 vcc, exec, s[8:9]
	v_pk_mul_f32 v[162:163], v[36:37], v[170:171] op_sel_hi:[1,0]
	v_pk_mul_f32 v[164:165], v[38:39], v[170:171] op_sel_hi:[1,0]
	v_pk_mul_f32 v[166:167], v[4:5], v[170:171] op_sel_hi:[1,0]
	v_pk_mul_f32 v[168:169], v[6:7], v[170:171] op_sel_hi:[1,0]
	v_exp_f32_e32 v162, v162
	v_exp_f32_e32 v163, v163
	v_exp_f32_e32 v164, v164
	v_exp_f32_e32 v165, v165
	v_exp_f32_e32 v166, v166
	v_exp_f32_e32 v167, v167
	v_exp_f32_e32 v168, v168
	v_exp_f32_e32 v169, v169
	v_pk_add_f32 v[162:163], v[162:163], v[172:173] op_sel_hi:[1,0]
	v_pk_add_f32 v[164:165], v[164:165], v[172:173] op_sel_hi:[1,0]
	v_pk_add_f32 v[166:167], v[166:167], v[172:173] op_sel_hi:[1,0]
	v_pk_add_f32 v[168:169], v[168:169], v[172:173] op_sel_hi:[1,0]
	v_rcp_f32_e32 v162, v162
	v_rcp_f32_e32 v163, v163
	v_rcp_f32_e32 v164, v164
	v_rcp_f32_e32 v165, v165
	v_rcp_f32_e32 v166, v166
	v_rcp_f32_e32 v167, v167
	v_rcp_f32_e32 v168, v168
	v_rcp_f32_e32 v169, v169
	v_pk_mul_f32 v[162:163], v[36:37], v[162:163]
	v_pk_mul_f32 v[164:165], v[38:39], v[164:165]
	v_pk_mul_f32 v[166:167], v[4:5], v[166:167]
	v_pk_mul_f32 v[168:169], v[6:7], v[168:169]
	v_pk_mul_f32 v[162:163], v[32:33], v[162:163]
	v_pk_mul_f32 v[164:165], v[34:35], v[164:165]
	v_pk_mul_f32 v[166:167], v[0:1], v[166:167]
	v_pk_mul_f32 v[168:169], v[2:3], v[168:169]
	v_cvt_pk_bf16_f32 v150, v162, v163
	v_cvt_pk_bf16_f32 v151, v164, v165
	v_cvt_pk_bf16_f32 v152, v166, v167
	v_cvt_pk_bf16_f32 v153, v168, v169
	global_store_dwordx4 v[144:145], v[150:153], off
	s_cbranch_vccz .LBB0_3081
	s_mov_b64 s[20:21], s[24:25]
	s_andn2_b64 vcc, exec, s[6:7]
	s_mov_b64 s[24:25], s[20:21]
	s_cbranch_vccnz .LBB0_3082
